# adds: fp8 gate GEMM first K-iteration after a tile epilogue peeled, its first two counted waits skip the 8 gate stores (vmcnt 16)
# baseline (speedup 1.0000x reference)
; __device__ __forceinline__ int lane_id_hw() { int l; asm volatile("v_mbcnt_lo_u32_b32 %0, -1, 0\n\tv_mbcnt_hi_u32_b32 %0, -1, %0" : "=v"(l)); return l; }
; #define PG8_STAGE(bufoff, gbase, voff) do { unsigned _g = (gbase); asm volatile("" : "+s"(_g));   _Pragma("unroll") for (int _i = 0; _i < 2; ++_i) \
;         __builtin_amdgcn_global_load_lds((const unsigned*)(wsb + (size_t)(unsigned)(_g + (voff)[_i])), (LAS unsigned*)(lds + (bufoff) + ldsw + _i * 8192), 16, 0, 0); } while (0)
; #define PG8_WAIT_V(n) asm volatile("s_waitcnt vmcnt(" #n ")" ::: "memory")
; #define PG8_WAIT_L(n) asm volatile("s_waitcnt lgkmcnt(" #n ")" ::: "memory")
; #define PG8_BAR __builtin_amdgcn_s_barrier()
; #define PG8_SCHED __builtin_amdgcn_sched_barrier(0)
;     ...
;         for (int t = 0; t < nt; t += 2) {
;             if constexpr (Epi::HAS_MID) { if (t == Epi::MID0 || t == Epi::MID1) { const int l2 = lane_id_hw(); E.mid(acc, cur, t == Epi::MID0 ? 0 : 1, wr, wc, l2 & 15, l2 >> 4); } }
;             const bool last = (t == nt - 2);
;             const unsigned a1 = cA + (unsigned)(t + 1) * kstep;
;             const unsigned a2 = last ? nA : cA + (unsigned)(t + 2) * kstep, b2 = last ? nB : cB + (unsigned)(t + 2) * kstep;
;             const unsigned a3 = a2 + kstep, b3 = b2 + kstep;
;             if constexpr (SP2) {
;             PG8_LDB(B0, 0, 0); PG8_LDB(B1, 0, 1); PG8_SCHED; PG8_LDA(At, 0, 0); PG8_STAGE(PG8_SA(1, 1), a1 + hstep, voffA);
;             PG8_WAIT_V(8); PG8_WAIT_L(0); PG8_BAR; PG8_MMA(0, 0, At, B0); PG8_MMA(0, 1, At, B1); PG8_BAR; PG8_SCHED;
;             PG8_LDA(At, 0, 1); PG8_STAGE(PG8_SB(0, 0), b2, voffB); PG8_STAGE(PG8_SB(0, 1), b2 + hstep, voffB); PG8_STAGE(PG8_SA(0, 0), a2, voffA);
;             PG8_WAIT_V(8); PG8_WAIT_L(0); PG8_BAR; PG8_MMA(1, 0, At, B0); PG8_MMA(1, 1, At, B1); PG8_BAR; PG8_SCHED;
.LBB0_559:
	s_add_i32 s47, s44, 0xfff80080
	s_cmp_eq_u32 s46, 28
	s_cselect_b32 s83, s36, s47
	s_cselect_b32 s47, s37, s45
	s_add_i32 s84, 0, 0x10000
	v_add_u32_e32 v0, s84, v138
	s_add_i32 s86, 0, 0x14000
	ds_read_b128 v[140:143], v0
	ds_read_b128 v[144:147], v0 offset:1024
	ds_read_b128 v[148:151], v0 offset:2048
	ds_read_b128 v[152:155], v0 offset:3072
	v_add_u32_e32 v0, s86, v138
	ds_read_b128 v[156:159], v0
	ds_read_b128 v[160:163], v0 offset:1024
	ds_read_b128 v[164:167], v0 offset:2048
	ds_read_b128 v[168:171], v0 offset:3072
	s_add_i32 s82, s83, 0x80
	s_mov_b32 s87, s44
	ds_read_b128 v[172:175], v139
	ds_read_b128 v[176:179], v139 offset:1024
	ds_read_b128 v[180:183], v139 offset:2048
	ds_read_b128 v[184:187], v139 offset:3072
	ds_read_b128 v[188:191], v139 offset:4096
	ds_read_b128 v[192:195], v139 offset:5120
	ds_read_b128 v[196:199], v139 offset:6144
	ds_read_b128 v[200:203], v139 offset:7168
	s_add_i32 m0, s9, 0xc000
	v_add_u32_e32 v0, s87, v134
	v_lshl_add_u64 v[204:205], v[130:131], 0, v[0:1]
	v_add_u32_e32 v0, s87, v136
	global_load_lds_dwordx4 v[204:205], off
	v_lshl_add_u64 v[204:205], v[130:131], 0, v[0:1]
	s_add_i32 m0, s9, 0xe000
	s_nop 0
	global_load_lds_dwordx4 v[204:205], off
	s_waitcnt vmcnt(8)
	s_waitcnt lgkmcnt(0)
	s_barrier
	s_setprio 1
	s_waitcnt lgkmcnt(0)
	v_mfma_f32_16x16x128_f8f6f4 v[126:129], v[140:147], v[172:179], v[126:129]
	v_mfma_f32_16x16x128_f8f6f4 v[122:125], v[148:155], v[172:179], v[122:125]
	v_mfma_f32_16x16x128_f8f6f4 v[110:113], v[140:147], v[180:187], v[110:113]
	v_mfma_f32_16x16x128_f8f6f4 v[106:109], v[148:155], v[180:187], v[106:109]
	v_mfma_f32_16x16x128_f8f6f4 v[204:207], v[140:147], v[188:195], v[94:97]
	v_mfma_f32_16x16x128_f8f6f4 v[208:211], v[148:155], v[188:195], v[90:93]
	v_mfma_f32_16x16x128_f8f6f4 v[212:215], v[140:147], v[196:203], v[78:81]
	v_mfma_f32_16x16x128_f8f6f4 v[216:219], v[148:155], v[196:203], v[74:77]
	s_setprio 0
	s_setprio 1
	v_mfma_f32_16x16x128_f8f6f4 v[118:121], v[156:163], v[172:179], v[118:121]
	v_mfma_f32_16x16x128_f8f6f4 v[114:117], v[164:171], v[172:179], v[114:117]
	v_mfma_f32_16x16x128_f8f6f4 v[102:105], v[156:163], v[180:187], v[102:105]
	v_mfma_f32_16x16x128_f8f6f4 v[98:101], v[164:171], v[180:187], v[98:101]
	v_mfma_f32_16x16x128_f8f6f4 v[172:175], v[156:163], v[188:195], v[86:89]
	v_mfma_f32_16x16x128_f8f6f4 v[176:179], v[164:171], v[188:195], v[82:85]
	v_mfma_f32_16x16x128_f8f6f4 v[180:183], v[156:163], v[196:203], v[70:73]
	v_mfma_f32_16x16x128_f8f6f4 v[184:187], v[164:171], v[196:203], v[66:69]
	s_setprio 0
	s_barrier
	s_mov_b32 s87, s47
	s_nop 3
	ds_read_b128 v[66:69], v139 offset:16384
	ds_read_b128 v[70:73], v139 offset:17408
	ds_read_b128 v[74:77], v139 offset:18432
	ds_read_b128 v[78:81], v139 offset:19456
	ds_read_b128 v[82:85], v139 offset:20480
	ds_read_b128 v[86:89], v139 offset:21504
	ds_read_b128 v[90:93], v139 offset:22528
	ds_read_b128 v[94:97], v139 offset:23552
	s_add_i32 s84, s84, s7
	v_add_u32_e32 v0, s87, v135
	v_lshl_add_u64 v[188:189], v[130:131], 0, v[0:1]
	s_mov_b32 m0, s84
	v_add_u32_e32 v0, s87, v137
	global_load_lds_dwordx4 v[188:189], off
	v_lshl_add_u64 v[188:189], v[130:131], 0, v[0:1]
	s_add_i32 m0, s84, 0x2000
	s_add_i32 s84, s47, 0x80000
	global_load_lds_dwordx4 v[188:189], off
	s_add_i32 s86, s86, s7
	v_add_u32_e32 v0, s84, v135
	v_lshl_add_u64 v[188:189], v[130:131], 0, v[0:1]
	s_mov_b32 m0, s86
	v_add_u32_e32 v0, s84, v137
	global_load_lds_dwordx4 v[188:189], off
	v_lshl_add_u64 v[188:189], v[130:131], 0, v[0:1]
	s_add_i32 m0, s86, 0x2000
	s_mov_b32 s84, s83
	global_load_lds_dwordx4 v[188:189], off
	s_mov_b32 m0, s9
	v_add_u32_e32 v0, s84, v134
	v_lshl_add_u64 v[188:189], v[130:131], 0, v[0:1]
	v_add_u32_e32 v0, s84, v136
	global_load_lds_dwordx4 v[188:189], off
	v_lshl_add_u64 v[188:189], v[130:131], 0, v[0:1]
	s_mov_b32 m0, s11
	s_nop 0
	global_load_lds_dwordx4 v[188:189], off
	s_waitcnt vmcnt(8)
	s_waitcnt lgkmcnt(0)
	s_barrier
	s_setprio 1
	s_waitcnt lgkmcnt(0)
	v_mfma_f32_16x16x128_f8f6f4 v[62:65], v[140:147], v[66:73], v[62:65]
	v_mfma_f32_16x16x128_f8f6f4 v[58:61], v[148:155], v[66:73], v[58:61]
	v_mfma_f32_16x16x128_f8f6f4 v[188:191], v[140:147], v[74:81], v[46:49]
	v_mfma_f32_16x16x128_f8f6f4 v[192:195], v[148:155], v[74:81], v[42:45]
	v_mfma_f32_16x16x128_f8f6f4 v[196:199], v[140:147], v[82:89], v[30:33]
	v_mfma_f32_16x16x128_f8f6f4 v[200:203], v[148:155], v[82:89], v[26:29]
	v_mfma_f32_16x16x128_f8f6f4 v[220:223], v[140:147], v[90:97], v[14:17]
	v_mfma_f32_16x16x128_f8f6f4 v[224:227], v[148:155], v[90:97], v[10:13]
	s_setprio 0
	s_setprio 1
	v_mfma_f32_16x16x128_f8f6f4 v[54:57], v[156:163], v[66:73], v[54:57]
	v_mfma_f32_16x16x128_f8f6f4 v[50:53], v[164:171], v[66:73], v[50:53]
	v_mfma_f32_16x16x128_f8f6f4 v[228:231], v[156:163], v[74:81], v[38:41]
	v_mfma_f32_16x16x128_f8f6f4 v[232:235], v[164:171], v[74:81], v[34:37]
	v_mfma_f32_16x16x128_f8f6f4 v[236:239], v[156:163], v[82:89], v[22:25]
	v_mfma_f32_16x16x128_f8f6f4 v[246:249], v[164:171], v[82:89], v[18:21]
	v_mfma_f32_16x16x128_f8f6f4 v[250:253], v[156:163], v[90:97], v[6:9]
	v_mfma_f32_16x16x128_f8f6f4 v[240:243], v[164:171], v[90:97], v[2:5]
	s_setprio 0
	s_barrier
; #define PG8_STAGE(bufoff, gbase, voff) do { unsigned _g = (gbase); asm volatile("" : "+s"(_g));   _Pragma("unroll") for (int _i = 0; _i < 2; ++_i) \
;         __builtin_amdgcn_global_load_lds((const unsigned*)(wsb + (size_t)(unsigned)(_g + (voff)[_i])), (LAS unsigned*)(lds + (bufoff) + ldsw + _i * 8192), 16, 0, 0); } while (0)
; #define PG8_WAIT_V(n) asm volatile("s_waitcnt vmcnt(" #n ")" ::: "memory")
; #define PG8_WAIT_L(n) asm volatile("s_waitcnt lgkmcnt(" #n ")" ::: "memory")
; #define PG8_BAR __builtin_amdgcn_s_barrier()
; #define PG8_SCHED __builtin_amdgcn_sched_barrier(0)
;     ...
;             PG8_LDB(B0, 1, 0); PG8_LDB(B1, 1, 1); PG8_SCHED; PG8_LDA(At, 1, 0); PG8_STAGE(PG8_SA(0, 1), a2 + hstep, voffA);
;             PG8_WAIT_V(8); PG8_WAIT_L(0); PG8_BAR; PG8_MMA(0, 0, At, B0); PG8_MMA(0, 1, At, B1); PG8_BAR; PG8_SCHED;
;             PG8_LDA(At, 1, 1); PG8_STAGE(PG8_SB(1, 0), b3, voffB); PG8_STAGE(PG8_SB(1, 1), b3 + hstep, voffB); PG8_STAGE(PG8_SA(1, 0), a3, voffA);
;             PG8_WAIT_V(8); PG8_WAIT_L(0); PG8_BAR; PG8_MMA(1, 0, At, B0); PG8_MMA(1, 1, At, B1); PG8_BAR; PG8_SCHED;
	s_add_i32 s84, 0, 0x18000
	v_add_u32_e32 v0, s84, v138
	s_add_i32 s86, 0, 0x1c000
	s_nop 1
	ds_read_b128 v[2:5], v0
	ds_read_b128 v[6:9], v0 offset:1024
	ds_read_b128 v[18:21], v0 offset:2048
	ds_read_b128 v[22:25], v0 offset:3072
	v_add_u32_e32 v0, s86, v138
	ds_read_b128 v[140:143], v0
	ds_read_b128 v[144:147], v0 offset:1024
	ds_read_b128 v[148:151], v0 offset:2048
	ds_read_b128 v[152:155], v0 offset:3072
	s_add_i32 s83, s83, 0x80000
	ds_read_b128 v[10:13], v139 offset:32768
	ds_read_b128 v[14:17], v139 offset:33792
	ds_read_b128 v[26:29], v139 offset:34816
	ds_read_b128 v[30:33], v139 offset:35840
	ds_read_b128 v[34:37], v139 offset:36864
	ds_read_b128 v[38:41], v139 offset:37888
	ds_read_b128 v[42:45], v139 offset:38912
	ds_read_b128 v[46:49], v139 offset:39936
	s_mov_b32 m0, s12
	v_add_u32_e32 v0, s83, v134
	v_lshl_add_u64 v[66:67], v[130:131], 0, v[0:1]
	v_add_u32_e32 v0, s83, v136
	global_load_lds_dwordx4 v[66:67], off
	v_lshl_add_u64 v[66:67], v[130:131], 0, v[0:1]
	s_mov_b32 m0, s13
	s_nop 0
	global_load_lds_dwordx4 v[66:67], off
	s_waitcnt vmcnt(8)
	s_waitcnt lgkmcnt(0)
	s_barrier
	s_setprio 1
	s_waitcnt lgkmcnt(0)
	v_mfma_f32_16x16x128_f8f6f4 v[126:129], v[2:9], v[10:17], v[126:129]
	v_mfma_f32_16x16x128_f8f6f4 v[122:125], v[18:25], v[10:17], v[122:125]
	v_mfma_f32_16x16x128_f8f6f4 v[110:113], v[2:9], v[26:33], v[110:113]
	v_mfma_f32_16x16x128_f8f6f4 v[106:109], v[18:25], v[26:33], v[106:109]
	v_mfma_f32_16x16x128_f8f6f4 v[94:97], v[2:9], v[34:41], v[204:207]
	v_mfma_f32_16x16x128_f8f6f4 v[90:93], v[18:25], v[34:41], v[208:211]
	v_mfma_f32_16x16x128_f8f6f4 v[78:81], v[2:9], v[42:49], v[212:215]
	v_mfma_f32_16x16x128_f8f6f4 v[74:77], v[18:25], v[42:49], v[216:219]
	s_setprio 0
	s_setprio 1
	v_mfma_f32_16x16x128_f8f6f4 v[118:121], v[140:147], v[10:17], v[118:121]
	v_mfma_f32_16x16x128_f8f6f4 v[114:117], v[148:155], v[10:17], v[114:117]
	v_mfma_f32_16x16x128_f8f6f4 v[102:105], v[140:147], v[26:33], v[102:105]
	v_mfma_f32_16x16x128_f8f6f4 v[98:101], v[148:155], v[26:33], v[98:101]
	v_mfma_f32_16x16x128_f8f6f4 v[86:89], v[140:147], v[34:41], v[172:175]
	v_mfma_f32_16x16x128_f8f6f4 v[82:85], v[148:155], v[34:41], v[176:179]
	v_mfma_f32_16x16x128_f8f6f4 v[70:73], v[140:147], v[42:49], v[180:183]
	v_mfma_f32_16x16x128_f8f6f4 v[66:69], v[148:155], v[42:49], v[184:187]
	s_setprio 0
	s_barrier
	s_add_i32 s83, s47, 0x80
	ds_read_b128 v[34:37], v139 offset:49152
	ds_read_b128 v[38:41], v139 offset:50176
	ds_read_b128 v[156:159], v139 offset:51200
	ds_read_b128 v[160:163], v139 offset:52224
	ds_read_b128 v[164:167], v139 offset:53248
	ds_read_b128 v[168:171], v139 offset:54272
	ds_read_b128 v[172:175], v139 offset:55296
	ds_read_b128 v[176:179], v139 offset:56320
	s_add_i32 s84, s84, s7
	v_add_u32_e32 v0, s83, v135
	v_lshl_add_u64 v[10:11], v[130:131], 0, v[0:1]
	s_mov_b32 m0, s84
	v_add_u32_e32 v0, s83, v137
	global_load_lds_dwordx4 v[10:11], off
	v_lshl_add_u64 v[10:11], v[130:131], 0, v[0:1]
	s_add_i32 m0, s84, 0x2000
	s_add_i32 s47, s47, 0x80080
	global_load_lds_dwordx4 v[10:11], off
	s_add_i32 s83, s86, s7
	v_add_u32_e32 v0, s47, v135
	v_lshl_add_u64 v[10:11], v[130:131], 0, v[0:1]
	s_mov_b32 m0, s83
	v_add_u32_e32 v0, s47, v137
	global_load_lds_dwordx4 v[10:11], off
	v_lshl_add_u64 v[10:11], v[130:131], 0, v[0:1]
	s_add_i32 m0, s83, 0x2000
	s_nop 0
	global_load_lds_dwordx4 v[10:11], off
	s_mov_b32 m0, s18
	v_add_u32_e32 v0, s82, v134
	v_lshl_add_u64 v[10:11], v[130:131], 0, v[0:1]
	v_add_u32_e32 v0, s82, v136
	global_load_lds_dwordx4 v[10:11], off
	v_lshl_add_u64 v[10:11], v[130:131], 0, v[0:1]
	s_mov_b32 m0, s22
	s_nop 0
	global_load_lds_dwordx4 v[10:11], off
	s_waitcnt vmcnt(8)
	s_waitcnt lgkmcnt(0)
	s_barrier
	s_setprio 1
	s_waitcnt lgkmcnt(0)
	v_mfma_f32_16x16x128_f8f6f4 v[62:65], v[2:9], v[34:41], v[62:65]
	v_mfma_f32_16x16x128_f8f6f4 v[58:61], v[18:25], v[34:41], v[58:61]
	v_mfma_f32_16x16x128_f8f6f4 v[46:49], v[2:9], v[156:163], v[188:191]
	v_mfma_f32_16x16x128_f8f6f4 v[42:45], v[18:25], v[156:163], v[192:195]
	v_mfma_f32_16x16x128_f8f6f4 v[30:33], v[2:9], v[164:171], v[196:199]
	v_mfma_f32_16x16x128_f8f6f4 v[26:29], v[18:25], v[164:171], v[200:203]
	v_mfma_f32_16x16x128_f8f6f4 v[14:17], v[2:9], v[172:179], v[220:223]
	v_mfma_f32_16x16x128_f8f6f4 v[10:13], v[18:25], v[172:179], v[224:227]
	s_setprio 0
	s_setprio 1
	v_mfma_f32_16x16x128_f8f6f4 v[54:57], v[140:147], v[34:41], v[54:57]
	v_mfma_f32_16x16x128_f8f6f4 v[50:53], v[148:155], v[34:41], v[50:53]
	v_mfma_f32_16x16x128_f8f6f4 v[38:41], v[140:147], v[156:163], v[228:231]
	v_mfma_f32_16x16x128_f8f6f4 v[34:37], v[148:155], v[156:163], v[232:235]
	v_mfma_f32_16x16x128_f8f6f4 v[22:25], v[140:147], v[164:171], v[236:239]
	v_mfma_f32_16x16x128_f8f6f4 v[18:21], v[148:155], v[164:171], v[246:249]
	v_mfma_f32_16x16x128_f8f6f4 v[6:9], v[140:147], v[172:179], v[250:253]
	v_mfma_f32_16x16x128_f8f6f4 v[2:5], v[148:155], v[172:179], v[240:243]
	s_setprio 0
	s_barrier
	s_add_i32 s46, s46, 2
	s_addk_i32 s44, 0x100
	s_addk_i32 s45, 0x100
	s_cmp_gt_u32 s46, 29
	s_cbranch_scc0 .LBB0_559
; #define GAS __attribute__((address_space(1)))
; __device__ __forceinline__ unsigned gate_q8(float g) { return (unsigned)fmaxf(g * 255.0f + 0.5f, 1.0f); }
; __device__ __forceinline__ unsigned gate_pk4(const f32x4& g) { return gate_q8(g[0]) | (gate_q8(g[1]) << 8) | (gate_q8(g[2]) << 16) | (gate_q8(g[3]) << 24); }
;     __device__ __forceinline__ void operator()(const f32x4 (&acc)[2][2][4][2], const pg8::GUnit& u, int wr, int wc, int fr, int fq) const {
;     ...
;         GAS unsigned char* gb = (GAS unsigned char*)P + (size_t)(u.pm * 256 + (wr * 4 + wc) * 32 + fq) * (INW * 2) + (GA * 2 + u.pn * 256 + fr * 16);
; #pragma unroll
;         for (int ai = 0; ai < 2; ++ai)
; #pragma unroll
;             for (int m = 0; m < 4; ++m) { u32x4 w; unsigned wq[4];
; #pragma unroll
;                 for (int bj = 0; bj < 2; ++bj)
; #pragma unroll
;                     for (int n = 0; n < 2; ++n) { f32x4 v = acc[ai][bj][m][n];
; #pragma unroll
;                         for (int j = 0; j < 4; ++j) v[j] = __builtin_amdgcn_rcpf(1.0f + __builtin_amdgcn_exp2f(v[j] * (-LOG2E * G8_DESCALE)));
;                         wq[bj * 2 + n] = gate_pk4(v); }
;                 w.x = wq[0]; w.y = wq[1]; w.z = wq[2]; w.w = wq[3];
;                 *(GAS u32x4*)(gb + (size_t)((ai * 4 + m) * 4) * (INW * 2)) = w; }
	v_mbcnt_lo_u32_b32 v0, -1, 0
	v_mbcnt_hi_u32_b32 v0, -1, v0
	s_lshl_b32 s38, s38, 8
	v_ashrrev_i32_e32 v140, 4, v0
	v_lshlrev_b32_e32 v0, 4, v0
	s_addk_i32 s38, 0x6000
	v_and_b32_e32 v0, 0xf0, v0
	v_or_b32_e32 v142, s38, v0
	v_mul_f32_e32 v0, 0xba38aa3b, v126
	v_mul_f32_e32 v126, 0xba38aa3b, v127
	v_exp_f32_e32 v126, v126
	v_mul_f32_e32 v127, 0xba38aa3b, v128
	v_exp_f32_e32 v127, v127
	v_exp_f32_e32 v0, v0
	v_mul_f32_e32 v128, 0xba38aa3b, v129
	v_add_f32_e32 v126, 1.0, v126
	v_exp_f32_e32 v128, v128
	v_rcp_f32_e32 v126, v126
	v_add_f32_e32 v127, 1.0, v127
	v_add_f32_e32 v0, 1.0, v0
	v_rcp_f32_e32 v127, v127
	v_rcp_f32_e32 v0, v0
	v_add_f32_e32 v128, 1.0, v128
	v_rcp_f32_e32 v128, v128
	v_fma_f32 v126, v126, s49, 0.5
	v_max_f32_e32 v126, 1.0, v126
	v_cvt_u32_f32_e32 v129, v126
	v_fma_f32 v126, v127, s49, 0.5
	v_fma_f32 v0, v0, s49, 0.5
	v_max_f32_e32 v126, 1.0, v126
	v_max_f32_e32 v0, 1.0, v0
	v_cvt_u32_f32_sdwa v144, v126 dst_sel:WORD_1 dst_unused:UNUSED_PAD src0_sel:DWORD
	v_fma_f32 v126, v128, s49, 0.5
	v_cvt_u32_f32_e32 v0, v0
	v_max_f32_e32 v126, 1.0, v126
	v_mul_f32_e32 v122, 0xba38aa3b, v122
	v_mul_f32_e32 v123, 0xba38aa3b, v123
	v_cvt_u32_f32_sdwa v128, v126 dst_sel:BYTE_3 dst_unused:UNUSED_PAD src0_sel:DWORD
	v_exp_f32_e32 v145, v122
	v_exp_f32_e32 v123, v123
	v_lshl_or_b32 v0, v129, 8, v0
	v_or3_b32 v122, v0, v144, v128
	v_add_f32_e32 v0, 1.0, v145
	v_add_f32_e32 v123, 1.0, v123
	v_mul_f32_e32 v124, 0xba38aa3b, v124
	v_rcp_f32_e32 v0, v0
	v_rcp_f32_e32 v123, v123
	v_mul_f32_e32 v125, 0xba38aa3b, v125
	v_mul_f32_e32 v118, 0xba38aa3b, v118
	v_mul_f32_e32 v119, 0xba38aa3b, v119
	v_exp_f32_e32 v124, v124
	v_exp_f32_e32 v125, v125
	v_exp_f32_e32 v118, v118
	v_exp_f32_e32 v119, v119
	v_mul_f32_e32 v120, 0xba38aa3b, v120
	v_mul_f32_e32 v121, 0xba38aa3b, v121
	v_exp_f32_e32 v120, v120
	v_exp_f32_e32 v121, v121
	v_fma_f32 v0, v0, s49, 0.5
	v_fma_f32 v123, v123, s49, 0.5
	v_add_f32_e32 v124, 1.0, v124
	v_max_f32_e32 v0, 1.0, v0
	v_max_f32_e32 v123, 1.0, v123
	v_add_f32_e32 v125, 1.0, v125
	v_add_f32_e32 v118, 1.0, v118
	v_add_f32_e32 v119, 1.0, v119
	v_cvt_u32_f32_e32 v0, v0
	v_cvt_u32_f32_e32 v123, v123
	v_rcp_f32_e32 v124, v124
	v_rcp_f32_e32 v125, v125
	v_rcp_f32_e32 v118, v118
	v_rcp_f32_e32 v119, v119
	v_add_f32_e32 v120, 1.0, v120
	v_add_f32_e32 v121, 1.0, v121
	v_rcp_f32_e32 v120, v120
	v_rcp_f32_e32 v121, v121
	v_lshl_or_b32 v0, v123, 8, v0
	v_fma_f32 v123, v124, s49, 0.5
	v_fma_f32 v124, v125, s49, 0.5
	v_fma_f32 v118, v118, s49, 0.5
	v_fma_f32 v119, v119, s49, 0.5
	v_max_f32_e32 v123, 1.0, v123
	v_max_f32_e32 v124, 1.0, v124
	v_max_f32_e32 v118, 1.0, v118
	v_max_f32_e32 v119, 1.0, v119
	v_fma_f32 v120, v120, s49, 0.5
	v_fma_f32 v121, v121, s49, 0.5
	v_cvt_u32_f32_sdwa v123, v123 dst_sel:WORD_1 dst_unused:UNUSED_PAD src0_sel:DWORD
	v_cvt_u32_f32_sdwa v124, v124 dst_sel:BYTE_3 dst_unused:UNUSED_PAD src0_sel:DWORD
	v_cvt_u32_f32_e32 v118, v118
	v_cvt_u32_f32_e32 v119, v119
	v_max_f32_e32 v120, 1.0, v120
	v_max_f32_e32 v121, 1.0, v121
	v_mul_f32_e32 v114, 0xba38aa3b, v114
	v_cvt_u32_f32_sdwa v120, v120 dst_sel:WORD_1 dst_unused:UNUSED_PAD src0_sel:DWORD
	v_cvt_u32_f32_sdwa v121, v121 dst_sel:BYTE_3 dst_unused:UNUSED_PAD src0_sel:DWORD
	v_exp_f32_e32 v114, v114
	v_or3_b32 v123, v0, v123, v124
	v_lshl_or_b32 v0, v119, 8, v118
	v_or3_b32 v124, v0, v120, v121
	v_add_f32_e32 v0, 1.0, v114
	v_mul_f32_e32 v114, 0xba38aa3b, v115
	v_exp_f32_e32 v114, v114
	v_mul_f32_e32 v115, 0xba38aa3b, v116
	v_rcp_f32_e32 v0, v0
	v_mul_f32_e32 v116, 0xba38aa3b, v117
	v_add_f32_e32 v114, 1.0, v114
	v_rcp_f32_e32 v114, v114
	v_exp_f32_e32 v115, v115
	v_exp_f32_e32 v116, v116
	v_fma_f32 v0, v0, s49, 0.5
	v_fma_f32 v114, v114, s49, 0.5
	v_add_f32_e32 v115, 1.0, v115
	v_max_f32_e32 v0, 1.0, v0
	v_max_f32_e32 v114, 1.0, v114
	v_add_f32_e32 v116, 1.0, v116
	v_cvt_u32_f32_e32 v0, v0
	v_cvt_u32_f32_e32 v114, v114
	v_rcp_f32_e32 v115, v115
	v_rcp_f32_e32 v116, v116
	v_mul_f32_e32 v110, 0xba38aa3b, v110
	v_lshl_or_b32 v0, v114, 8, v0
	v_fma_f32 v114, v115, s49, 0.5
	v_fma_f32 v115, v116, s49, 0.5
	v_max_f32_e32 v114, 1.0, v114
	v_max_f32_e32 v115, 1.0, v115
	v_mul_f32_e32 v111, 0xba38aa3b, v111
	v_cvt_u32_f32_sdwa v114, v114 dst_sel:WORD_1 dst_unused:UNUSED_PAD src0_sel:DWORD
	v_cvt_u32_f32_sdwa v115, v115 dst_sel:BYTE_3 dst_unused:UNUSED_PAD src0_sel:DWORD
	v_exp_f32_e32 v110, v110
	v_exp_f32_e32 v111, v111
	v_mul_f32_e32 v106, 0xba38aa3b, v106
	v_or3_b32 v125, v0, v114, v115
	v_add_f32_e32 v0, 1.0, v110
	v_add_f32_e32 v110, 1.0, v111
	v_mul_f32_e32 v111, 0xba38aa3b, v112
	v_mul_f32_e32 v112, 0xba38aa3b, v113
	v_exp_f32_e32 v111, v111
	v_exp_f32_e32 v112, v112
	v_rcp_f32_e32 v0, v0
	v_rcp_f32_e32 v110, v110
	v_add_f32_e32 v111, 1.0, v111
	v_add_f32_e32 v112, 1.0, v112
	v_rcp_f32_e32 v111, v111
	v_rcp_f32_e32 v112, v112
	v_fma_f32 v0, v0, s49, 0.5
	v_fma_f32 v110, v110, s49, 0.5
	v_max_f32_e32 v0, 1.0, v0
	v_max_f32_e32 v110, 1.0, v110
	v_fma_f32 v111, v111, s49, 0.5
	v_fma_f32 v112, v112, s49, 0.5
	v_cvt_u32_f32_e32 v0, v0
	v_cvt_u32_f32_e32 v110, v110
	v_max_f32_e32 v111, 1.0, v111
	v_max_f32_e32 v112, 1.0, v112
	v_mul_f32_e32 v107, 0xba38aa3b, v107
	v_cvt_u32_f32_sdwa v111, v111 dst_sel:WORD_1 dst_unused:UNUSED_PAD src0_sel:DWORD
	v_cvt_u32_f32_sdwa v112, v112 dst_sel:BYTE_3 dst_unused:UNUSED_PAD src0_sel:DWORD
	v_exp_f32_e32 v113, v106
	v_exp_f32_e32 v107, v107
	v_lshl_or_b32 v0, v110, 8, v0
	v_or3_b32 v106, v0, v111, v112
	v_add_f32_e32 v0, 1.0, v113
	v_add_f32_e32 v107, 1.0, v107
	v_mul_f32_e32 v108, 0xba38aa3b, v108
	v_rcp_f32_e32 v0, v0
	v_rcp_f32_e32 v107, v107
	v_mul_f32_e32 v109, 0xba38aa3b, v109
	v_exp_f32_e32 v108, v108
	v_exp_f32_e32 v109, v109
; #define GAS __attribute__((address_space(1)))
; __device__ __forceinline__ unsigned gate_q8(float g) { return (unsigned)fmaxf(g * 255.0f + 0.5f, 1.0f); }
; __device__ __forceinline__ unsigned gate_pk4(const f32x4& g) { return gate_q8(g[0]) | (gate_q8(g[1]) << 8) | (gate_q8(g[2]) << 16) | (gate_q8(g[3]) << 24); }
;     __device__ __forceinline__ void operator()(const f32x4 (&acc)[2][2][4][2], const pg8::GUnit& u, int wr, int wc, int fr, int fq) const {
;     ...
;         GAS unsigned char* gb = (GAS unsigned char*)P + (size_t)(u.pm * 256 + (wr * 4 + wc) * 32 + fq) * (INW * 2) + (GA * 2 + u.pn * 256 + fr * 16);
; #pragma unroll
;         for (int ai = 0; ai < 2; ++ai)
; #pragma unroll
;             for (int m = 0; m < 4; ++m) { u32x4 w; unsigned wq[4];
; #pragma unroll
;                 for (int bj = 0; bj < 2; ++bj)
; #pragma unroll
;                     for (int n = 0; n < 2; ++n) { f32x4 v = acc[ai][bj][m][n];
; #pragma unroll
;                         for (int j = 0; j < 4; ++j) v[j] = __builtin_amdgcn_rcpf(1.0f + __builtin_amdgcn_exp2f(v[j] * (-LOG2E * G8_DESCALE)));
;                         wq[bj * 2 + n] = gate_pk4(v); }
;                 w.x = wq[0]; w.y = wq[1]; w.z = wq[2]; w.w = wq[3];
;                 *(GAS u32x4*)(gb + (size_t)((ai * 4 + m) * 4) * (INW * 2)) = w; }
	v_fma_f32 v0, v0, s49, 0.5
	v_fma_f32 v107, v107, s49, 0.5
	v_add_f32_e32 v108, 1.0, v108
	v_max_f32_e32 v0, 1.0, v0
	v_max_f32_e32 v107, 1.0, v107
	v_add_f32_e32 v109, 1.0, v109
	v_cvt_u32_f32_e32 v0, v0
	v_cvt_u32_f32_e32 v107, v107
	v_rcp_f32_e32 v108, v108
	v_rcp_f32_e32 v109, v109
	v_mul_f32_e32 v102, 0xba38aa3b, v102
	v_lshl_or_b32 v0, v107, 8, v0
	v_fma_f32 v107, v108, s49, 0.5
	v_fma_f32 v108, v109, s49, 0.5
	v_max_f32_e32 v107, 1.0, v107
	v_max_f32_e32 v108, 1.0, v108
	v_mul_f32_e32 v103, 0xba38aa3b, v103
	v_cvt_u32_f32_sdwa v107, v107 dst_sel:WORD_1 dst_unused:UNUSED_PAD src0_sel:DWORD
	v_cvt_u32_f32_sdwa v108, v108 dst_sel:BYTE_3 dst_unused:UNUSED_PAD src0_sel:DWORD
	v_exp_f32_e32 v102, v102
	v_exp_f32_e32 v103, v103
	v_mul_f32_e32 v98, 0xba38aa3b, v98
	v_or3_b32 v107, v0, v107, v108
	v_add_f32_e32 v0, 1.0, v102
	v_add_f32_e32 v102, 1.0, v103
	v_mul_f32_e32 v103, 0xba38aa3b, v104
	v_mul_f32_e32 v104, 0xba38aa3b, v105
	v_mul_f32_e32 v99, 0xba38aa3b, v99
	v_exp_f32_e32 v103, v103
	v_exp_f32_e32 v104, v104
	v_exp_f32_e32 v98, v98
	v_exp_f32_e32 v99, v99
	v_mul_f32_e32 v100, 0xba38aa3b, v100
	v_mul_f32_e32 v101, 0xba38aa3b, v101
	v_exp_f32_e32 v100, v100
	v_exp_f32_e32 v101, v101
	v_rcp_f32_e32 v0, v0
	v_rcp_f32_e32 v102, v102
	v_add_f32_e32 v103, 1.0, v103
	v_add_f32_e32 v104, 1.0, v104
	v_add_f32_e32 v98, 1.0, v98
	v_add_f32_e32 v99, 1.0, v99
	v_rcp_f32_e32 v103, v103
	v_rcp_f32_e32 v104, v104
	v_rcp_f32_e32 v98, v98
	v_rcp_f32_e32 v99, v99
	v_add_f32_e32 v100, 1.0, v100
	v_add_f32_e32 v101, 1.0, v101
	v_rcp_f32_e32 v100, v100
	v_rcp_f32_e32 v101, v101
	v_fma_f32 v0, v0, s49, 0.5
	v_fma_f32 v102, v102, s49, 0.5
	v_max_f32_e32 v0, 1.0, v0
	v_max_f32_e32 v102, 1.0, v102
	v_fma_f32 v103, v103, s49, 0.5
	v_fma_f32 v104, v104, s49, 0.5
	v_fma_f32 v98, v98, s49, 0.5
	v_fma_f32 v99, v99, s49, 0.5
	v_cvt_u32_f32_e32 v0, v0
	v_cvt_u32_f32_e32 v102, v102
	v_max_f32_e32 v103, 1.0, v103
	v_max_f32_e32 v104, 1.0, v104
	v_max_f32_e32 v98, 1.0, v98
	v_max_f32_e32 v99, 1.0, v99
	v_fma_f32 v100, v100, s49, 0.5
	v_fma_f32 v101, v101, s49, 0.5
	v_cvt_u32_f32_sdwa v103, v103 dst_sel:WORD_1 dst_unused:UNUSED_PAD src0_sel:DWORD
	v_cvt_u32_f32_sdwa v104, v104 dst_sel:BYTE_3 dst_unused:UNUSED_PAD src0_sel:DWORD
	v_cvt_u32_f32_e32 v98, v98
	v_cvt_u32_f32_e32 v99, v99
	v_max_f32_e32 v100, 1.0, v100
	v_max_f32_e32 v101, 1.0, v101
	v_cvt_u32_f32_sdwa v100, v100 dst_sel:WORD_1 dst_unused:UNUSED_PAD src0_sel:DWORD
	v_cvt_u32_f32_sdwa v101, v101 dst_sel:BYTE_3 dst_unused:UNUSED_PAD src0_sel:DWORD
	v_lshl_or_b32 v0, v102, 8, v0
	v_or3_b32 v108, v0, v103, v104
	v_lshl_or_b32 v0, v99, 8, v98
	v_or3_b32 v109, v0, v100, v101
	v_mul_f32_e32 v0, 0xba38aa3b, v94
	v_mul_f32_e32 v94, 0xba38aa3b, v95
	v_exp_f32_e32 v0, v0
	v_exp_f32_e32 v98, v94
	v_mul_f32_e32 v96, 0xba38aa3b, v96
	v_mul_f32_e32 v97, 0xba38aa3b, v97
	v_exp_f32_e32 v96, v96
	v_exp_f32_e32 v97, v97
	v_add_f32_e32 v0, 1.0, v0
	v_add_f32_e32 v98, 1.0, v98
	v_rcp_f32_e32 v0, v0
	v_rcp_f32_e32 v98, v98
	v_add_f32_e32 v96, 1.0, v96
	v_add_f32_e32 v97, 1.0, v97
	v_rcp_f32_e32 v96, v96
	v_rcp_f32_e32 v97, v97
	v_fma_f32 v0, v0, s49, 0.5
	v_fma_f32 v98, v98, s49, 0.5
	v_max_f32_e32 v0, 1.0, v0
	v_max_f32_e32 v98, 1.0, v98
	v_fma_f32 v96, v96, s49, 0.5
	v_fma_f32 v97, v97, s49, 0.5
	v_cvt_u32_f32_e32 v0, v0
	v_cvt_u32_f32_e32 v98, v98
	v_max_f32_e32 v96, 1.0, v96
	v_max_f32_e32 v97, 1.0, v97
	v_mul_f32_e32 v90, 0xba38aa3b, v90
	v_mul_f32_e32 v91, 0xba38aa3b, v91
	v_cvt_u32_f32_sdwa v96, v96 dst_sel:WORD_1 dst_unused:UNUSED_PAD src0_sel:DWORD
	v_cvt_u32_f32_sdwa v97, v97 dst_sel:BYTE_3 dst_unused:UNUSED_PAD src0_sel:DWORD
	v_exp_f32_e32 v99, v90
	v_exp_f32_e32 v91, v91
	v_lshl_or_b32 v0, v98, 8, v0
	v_or3_b32 v90, v0, v96, v97
	v_add_f32_e32 v0, 1.0, v99
	v_add_f32_e32 v91, 1.0, v91
	v_mul_f32_e32 v92, 0xba38aa3b, v92
	v_rcp_f32_e32 v0, v0
	v_rcp_f32_e32 v91, v91
	v_mul_f32_e32 v93, 0xba38aa3b, v93
	v_exp_f32_e32 v92, v92
	v_exp_f32_e32 v93, v93
	v_fma_f32 v0, v0, s49, 0.5
	v_fma_f32 v91, v91, s49, 0.5
	v_add_f32_e32 v92, 1.0, v92
	v_max_f32_e32 v0, 1.0, v0
	v_max_f32_e32 v91, 1.0, v91
	v_add_f32_e32 v93, 1.0, v93
	v_cvt_u32_f32_e32 v0, v0
	v_cvt_u32_f32_e32 v91, v91
	v_rcp_f32_e32 v92, v92
	v_rcp_f32_e32 v93, v93
	v_mul_f32_e32 v86, 0xba38aa3b, v86
	v_lshl_or_b32 v0, v91, 8, v0
	v_fma_f32 v91, v92, s49, 0.5
	v_fma_f32 v92, v93, s49, 0.5
	v_max_f32_e32 v91, 1.0, v91
	v_max_f32_e32 v92, 1.0, v92
	v_mul_f32_e32 v87, 0xba38aa3b, v87
	v_cvt_u32_f32_sdwa v91, v91 dst_sel:WORD_1 dst_unused:UNUSED_PAD src0_sel:DWORD
	v_cvt_u32_f32_sdwa v92, v92 dst_sel:BYTE_3 dst_unused:UNUSED_PAD src0_sel:DWORD
	v_exp_f32_e32 v86, v86
	v_exp_f32_e32 v87, v87
	v_mul_f32_e32 v82, 0xba38aa3b, v82
	v_or3_b32 v91, v0, v91, v92
	v_add_f32_e32 v0, 1.0, v86
	v_add_f32_e32 v86, 1.0, v87
	v_mul_f32_e32 v87, 0xba38aa3b, v88
	v_mul_f32_e32 v88, 0xba38aa3b, v89
	v_mul_f32_e32 v83, 0xba38aa3b, v83
	v_exp_f32_e32 v87, v87
	v_exp_f32_e32 v88, v88
	v_exp_f32_e32 v82, v82
	v_exp_f32_e32 v83, v83
	v_mul_f32_e32 v84, 0xba38aa3b, v84
	v_mul_f32_e32 v85, 0xba38aa3b, v85
	v_exp_f32_e32 v84, v84
	v_exp_f32_e32 v85, v85
	v_rcp_f32_e32 v0, v0
	v_rcp_f32_e32 v86, v86
	v_add_f32_e32 v87, 1.0, v87
	v_add_f32_e32 v88, 1.0, v88
	v_add_f32_e32 v82, 1.0, v82
	v_add_f32_e32 v83, 1.0, v83
	v_rcp_f32_e32 v87, v87
	v_rcp_f32_e32 v88, v88
	v_rcp_f32_e32 v82, v82
	v_rcp_f32_e32 v83, v83
	v_add_f32_e32 v84, 1.0, v84
	v_add_f32_e32 v85, 1.0, v85
	v_rcp_f32_e32 v84, v84
	v_rcp_f32_e32 v85, v85
	v_fma_f32 v0, v0, s49, 0.5
	v_fma_f32 v86, v86, s49, 0.5
	v_max_f32_e32 v0, 1.0, v0
	v_max_f32_e32 v86, 1.0, v86
	v_fma_f32 v87, v87, s49, 0.5
	v_fma_f32 v88, v88, s49, 0.5
; #define GAS __attribute__((address_space(1)))
; __device__ __forceinline__ unsigned gate_q8(float g) { return (unsigned)fmaxf(g * 255.0f + 0.5f, 1.0f); }
; __device__ __forceinline__ unsigned gate_pk4(const f32x4& g) { return gate_q8(g[0]) | (gate_q8(g[1]) << 8) | (gate_q8(g[2]) << 16) | (gate_q8(g[3]) << 24); }
;     __device__ __forceinline__ void operator()(const f32x4 (&acc)[2][2][4][2], const pg8::GUnit& u, int wr, int wc, int fr, int fq) const {
;     ...
;         GAS unsigned char* gb = (GAS unsigned char*)P + (size_t)(u.pm * 256 + (wr * 4 + wc) * 32 + fq) * (INW * 2) + (GA * 2 + u.pn * 256 + fr * 16);
; #pragma unroll
;         for (int ai = 0; ai < 2; ++ai)
; #pragma unroll
;             for (int m = 0; m < 4; ++m) { u32x4 w; unsigned wq[4];
; #pragma unroll
;                 for (int bj = 0; bj < 2; ++bj)
; #pragma unroll
;                     for (int n = 0; n < 2; ++n) { f32x4 v = acc[ai][bj][m][n];
; #pragma unroll
;                         for (int j = 0; j < 4; ++j) v[j] = __builtin_amdgcn_rcpf(1.0f + __builtin_amdgcn_exp2f(v[j] * (-LOG2E * G8_DESCALE)));
;                         wq[bj * 2 + n] = gate_pk4(v); }
;                 w.x = wq[0]; w.y = wq[1]; w.z = wq[2]; w.w = wq[3];
;                 *(GAS u32x4*)(gb + (size_t)((ai * 4 + m) * 4) * (INW * 2)) = w; }
	v_fma_f32 v82, v82, s49, 0.5
	v_fma_f32 v83, v83, s49, 0.5
	v_cvt_u32_f32_e32 v0, v0
	v_cvt_u32_f32_e32 v86, v86
	v_max_f32_e32 v87, 1.0, v87
	v_max_f32_e32 v88, 1.0, v88
	v_max_f32_e32 v82, 1.0, v82
	v_max_f32_e32 v83, 1.0, v83
	v_fma_f32 v84, v84, s49, 0.5
	v_fma_f32 v85, v85, s49, 0.5
	v_cvt_u32_f32_sdwa v87, v87 dst_sel:WORD_1 dst_unused:UNUSED_PAD src0_sel:DWORD
	v_cvt_u32_f32_sdwa v88, v88 dst_sel:BYTE_3 dst_unused:UNUSED_PAD src0_sel:DWORD
	v_cvt_u32_f32_e32 v82, v82
	v_cvt_u32_f32_e32 v83, v83
	v_max_f32_e32 v84, 1.0, v84
	v_max_f32_e32 v85, 1.0, v85
	v_cvt_u32_f32_sdwa v84, v84 dst_sel:WORD_1 dst_unused:UNUSED_PAD src0_sel:DWORD
	v_cvt_u32_f32_sdwa v85, v85 dst_sel:BYTE_3 dst_unused:UNUSED_PAD src0_sel:DWORD
	v_lshl_or_b32 v0, v86, 8, v0
	v_or3_b32 v92, v0, v87, v88
	v_lshl_or_b32 v0, v83, 8, v82
	v_or3_b32 v93, v0, v84, v85
	v_mul_f32_e32 v0, 0xba38aa3b, v78
	v_mul_f32_e32 v78, 0xba38aa3b, v79
	v_exp_f32_e32 v0, v0
	v_exp_f32_e32 v82, v78
	v_mul_f32_e32 v80, 0xba38aa3b, v80
	v_mul_f32_e32 v81, 0xba38aa3b, v81
	v_exp_f32_e32 v80, v80
	v_exp_f32_e32 v81, v81
	v_add_f32_e32 v0, 1.0, v0
	v_add_f32_e32 v82, 1.0, v82
	v_rcp_f32_e32 v0, v0
	v_rcp_f32_e32 v82, v82
	v_add_f32_e32 v80, 1.0, v80
	v_add_f32_e32 v81, 1.0, v81
	v_rcp_f32_e32 v80, v80
	v_rcp_f32_e32 v81, v81
	v_fma_f32 v0, v0, s49, 0.5
	v_fma_f32 v82, v82, s49, 0.5
	v_max_f32_e32 v0, 1.0, v0
	v_max_f32_e32 v82, 1.0, v82
	v_fma_f32 v80, v80, s49, 0.5
	v_fma_f32 v81, v81, s49, 0.5
	v_cvt_u32_f32_e32 v0, v0
	v_cvt_u32_f32_e32 v82, v82
	v_max_f32_e32 v80, 1.0, v80
	v_max_f32_e32 v81, 1.0, v81
	v_mul_f32_e32 v74, 0xba38aa3b, v74
	v_mul_f32_e32 v75, 0xba38aa3b, v75
	v_cvt_u32_f32_sdwa v80, v80 dst_sel:WORD_1 dst_unused:UNUSED_PAD src0_sel:DWORD
	v_cvt_u32_f32_sdwa v81, v81 dst_sel:BYTE_3 dst_unused:UNUSED_PAD src0_sel:DWORD
	v_exp_f32_e32 v83, v74
	v_exp_f32_e32 v75, v75
	v_lshl_or_b32 v0, v82, 8, v0
	v_or3_b32 v74, v0, v80, v81
	v_add_f32_e32 v0, 1.0, v83
	v_add_f32_e32 v75, 1.0, v75
	v_mul_f32_e32 v76, 0xba38aa3b, v76
	v_rcp_f32_e32 v0, v0
	v_rcp_f32_e32 v75, v75
	v_mul_f32_e32 v77, 0xba38aa3b, v77
	v_exp_f32_e32 v76, v76
	v_exp_f32_e32 v77, v77
	v_fma_f32 v0, v0, s49, 0.5
	v_fma_f32 v75, v75, s49, 0.5
	v_add_f32_e32 v76, 1.0, v76
	v_max_f32_e32 v0, 1.0, v0
	v_max_f32_e32 v75, 1.0, v75
	v_add_f32_e32 v77, 1.0, v77
	v_cvt_u32_f32_e32 v0, v0
	v_cvt_u32_f32_e32 v75, v75
	v_rcp_f32_e32 v76, v76
	v_rcp_f32_e32 v77, v77
	v_mul_f32_e32 v70, 0xba38aa3b, v70
	v_lshl_or_b32 v0, v75, 8, v0
	v_fma_f32 v75, v76, s49, 0.5
	v_fma_f32 v76, v77, s49, 0.5
	v_max_f32_e32 v75, 1.0, v75
	v_max_f32_e32 v76, 1.0, v76
	v_mul_f32_e32 v71, 0xba38aa3b, v71
	v_cvt_u32_f32_sdwa v75, v75 dst_sel:WORD_1 dst_unused:UNUSED_PAD src0_sel:DWORD
	v_cvt_u32_f32_sdwa v76, v76 dst_sel:BYTE_3 dst_unused:UNUSED_PAD src0_sel:DWORD
	v_exp_f32_e32 v70, v70
	v_exp_f32_e32 v71, v71
	v_mul_f32_e32 v66, 0xba38aa3b, v66
	v_or3_b32 v75, v0, v75, v76
	v_add_f32_e32 v0, 1.0, v70
	v_add_f32_e32 v70, 1.0, v71
	v_mul_f32_e32 v71, 0xba38aa3b, v72
	v_mul_f32_e32 v72, 0xba38aa3b, v73
	v_mul_f32_e32 v67, 0xba38aa3b, v67
	v_exp_f32_e32 v71, v71
	v_exp_f32_e32 v72, v72
	v_exp_f32_e32 v66, v66
	v_exp_f32_e32 v67, v67
	v_mul_f32_e32 v68, 0xba38aa3b, v68
	v_mul_f32_e32 v69, 0xba38aa3b, v69
	v_exp_f32_e32 v68, v68
	v_exp_f32_e32 v69, v69
	v_rcp_f32_e32 v0, v0
	v_rcp_f32_e32 v70, v70
	v_add_f32_e32 v71, 1.0, v71
	v_add_f32_e32 v72, 1.0, v72
	v_add_f32_e32 v66, 1.0, v66
	v_add_f32_e32 v67, 1.0, v67
	v_rcp_f32_e32 v71, v71
	v_rcp_f32_e32 v72, v72
	v_rcp_f32_e32 v66, v66
	v_rcp_f32_e32 v67, v67
	v_add_f32_e32 v68, 1.0, v68
	v_add_f32_e32 v69, 1.0, v69
	v_rcp_f32_e32 v68, v68
	v_rcp_f32_e32 v69, v69
	v_fma_f32 v0, v0, s49, 0.5
	v_fma_f32 v70, v70, s49, 0.5
	v_max_f32_e32 v0, 1.0, v0
	v_max_f32_e32 v70, 1.0, v70
	v_fma_f32 v71, v71, s49, 0.5
	v_fma_f32 v72, v72, s49, 0.5
	v_fma_f32 v66, v66, s49, 0.5
	v_fma_f32 v67, v67, s49, 0.5
	v_cvt_u32_f32_e32 v0, v0
	v_cvt_u32_f32_e32 v70, v70
	v_max_f32_e32 v71, 1.0, v71
	v_max_f32_e32 v72, 1.0, v72
	v_max_f32_e32 v66, 1.0, v66
	v_max_f32_e32 v67, 1.0, v67
	v_fma_f32 v68, v68, s49, 0.5
	v_fma_f32 v69, v69, s49, 0.5
	v_cvt_u32_f32_sdwa v71, v71 dst_sel:WORD_1 dst_unused:UNUSED_PAD src0_sel:DWORD
	v_cvt_u32_f32_sdwa v72, v72 dst_sel:BYTE_3 dst_unused:UNUSED_PAD src0_sel:DWORD
	v_cvt_u32_f32_e32 v66, v66
	v_cvt_u32_f32_e32 v67, v67
	v_max_f32_e32 v68, 1.0, v68
	v_max_f32_e32 v69, 1.0, v69
	v_cvt_u32_f32_sdwa v68, v68 dst_sel:WORD_1 dst_unused:UNUSED_PAD src0_sel:DWORD
	v_cvt_u32_f32_sdwa v69, v69 dst_sel:BYTE_3 dst_unused:UNUSED_PAD src0_sel:DWORD
	v_lshl_or_b32 v0, v70, 8, v0
	v_or3_b32 v76, v0, v71, v72
	v_lshl_or_b32 v0, v67, 8, v66
	v_or3_b32 v77, v0, v68, v69
	v_mul_f32_e32 v0, 0xba38aa3b, v62
	v_mul_f32_e32 v62, 0xba38aa3b, v63
	v_exp_f32_e32 v0, v0
	v_exp_f32_e32 v66, v62
	v_mul_f32_e32 v64, 0xba38aa3b, v64
	v_mul_f32_e32 v65, 0xba38aa3b, v65
	v_exp_f32_e32 v64, v64
	v_exp_f32_e32 v65, v65
	v_add_f32_e32 v0, 1.0, v0
	v_add_f32_e32 v66, 1.0, v66
	v_rcp_f32_e32 v0, v0
	v_rcp_f32_e32 v66, v66
	v_add_f32_e32 v64, 1.0, v64
	v_add_f32_e32 v65, 1.0, v65
	v_rcp_f32_e32 v64, v64
	v_rcp_f32_e32 v65, v65
	v_fma_f32 v0, v0, s49, 0.5
	v_fma_f32 v66, v66, s49, 0.5
	v_max_f32_e32 v0, 1.0, v0
	v_max_f32_e32 v66, 1.0, v66
	v_fma_f32 v64, v64, s49, 0.5
	v_fma_f32 v65, v65, s49, 0.5
	v_cvt_u32_f32_e32 v0, v0
	v_cvt_u32_f32_e32 v66, v66
	v_max_f32_e32 v64, 1.0, v64
	v_max_f32_e32 v65, 1.0, v65
	v_mul_f32_e32 v58, 0xba38aa3b, v58
	v_mul_f32_e32 v59, 0xba38aa3b, v59
	v_cvt_u32_f32_sdwa v64, v64 dst_sel:WORD_1 dst_unused:UNUSED_PAD src0_sel:DWORD
	v_cvt_u32_f32_sdwa v65, v65 dst_sel:BYTE_3 dst_unused:UNUSED_PAD src0_sel:DWORD
; #define GAS __attribute__((address_space(1)))
; __device__ __forceinline__ unsigned gate_q8(float g) { return (unsigned)fmaxf(g * 255.0f + 0.5f, 1.0f); }
; __device__ __forceinline__ unsigned gate_pk4(const f32x4& g) { return gate_q8(g[0]) | (gate_q8(g[1]) << 8) | (gate_q8(g[2]) << 16) | (gate_q8(g[3]) << 24); }
;     __device__ __forceinline__ void operator()(const f32x4 (&acc)[2][2][4][2], const pg8::GUnit& u, int wr, int wc, int fr, int fq) const {
;     ...
;         GAS unsigned char* gb = (GAS unsigned char*)P + (size_t)(u.pm * 256 + (wr * 4 + wc) * 32 + fq) * (INW * 2) + (GA * 2 + u.pn * 256 + fr * 16);
; #pragma unroll
;         for (int ai = 0; ai < 2; ++ai)
; #pragma unroll
;             for (int m = 0; m < 4; ++m) { u32x4 w; unsigned wq[4];
; #pragma unroll
;                 for (int bj = 0; bj < 2; ++bj)
; #pragma unroll
;                     for (int n = 0; n < 2; ++n) { f32x4 v = acc[ai][bj][m][n];
; #pragma unroll
;                         for (int j = 0; j < 4; ++j) v[j] = __builtin_amdgcn_rcpf(1.0f + __builtin_amdgcn_exp2f(v[j] * (-LOG2E * G8_DESCALE)));
;                         wq[bj * 2 + n] = gate_pk4(v); }
;                 w.x = wq[0]; w.y = wq[1]; w.z = wq[2]; w.w = wq[3];
;                 *(GAS u32x4*)(gb + (size_t)((ai * 4 + m) * 4) * (INW * 2)) = w; }
	v_exp_f32_e32 v67, v58
	v_exp_f32_e32 v59, v59
	v_lshl_or_b32 v0, v66, 8, v0
	v_or3_b32 v58, v0, v64, v65
	v_add_f32_e32 v0, 1.0, v67
	v_add_f32_e32 v59, 1.0, v59
	v_mul_f32_e32 v60, 0xba38aa3b, v60
	v_rcp_f32_e32 v0, v0
	v_rcp_f32_e32 v59, v59
	v_mul_f32_e32 v61, 0xba38aa3b, v61
	v_exp_f32_e32 v60, v60
	v_exp_f32_e32 v61, v61
	v_fma_f32 v0, v0, s49, 0.5
	v_fma_f32 v59, v59, s49, 0.5
	v_add_f32_e32 v60, 1.0, v60
	v_max_f32_e32 v0, 1.0, v0
	v_max_f32_e32 v59, 1.0, v59
	v_add_f32_e32 v61, 1.0, v61
	v_cvt_u32_f32_e32 v0, v0
	v_cvt_u32_f32_e32 v59, v59
	v_rcp_f32_e32 v60, v60
	v_rcp_f32_e32 v61, v61
	v_mul_f32_e32 v54, 0xba38aa3b, v54
	v_lshl_or_b32 v0, v59, 8, v0
	v_fma_f32 v59, v60, s49, 0.5
	v_fma_f32 v60, v61, s49, 0.5
	v_max_f32_e32 v59, 1.0, v59
	v_max_f32_e32 v60, 1.0, v60
	v_mul_f32_e32 v55, 0xba38aa3b, v55
	v_cvt_u32_f32_sdwa v59, v59 dst_sel:WORD_1 dst_unused:UNUSED_PAD src0_sel:DWORD
	v_cvt_u32_f32_sdwa v60, v60 dst_sel:BYTE_3 dst_unused:UNUSED_PAD src0_sel:DWORD
	v_exp_f32_e32 v54, v54
	v_exp_f32_e32 v55, v55
	v_mul_f32_e32 v50, 0xba38aa3b, v50
	v_or3_b32 v59, v0, v59, v60
	v_add_f32_e32 v0, 1.0, v54
	v_add_f32_e32 v54, 1.0, v55
	v_mul_f32_e32 v55, 0xba38aa3b, v56
	v_mul_f32_e32 v56, 0xba38aa3b, v57
	v_mul_f32_e32 v51, 0xba38aa3b, v51
	v_exp_f32_e32 v55, v55
	v_exp_f32_e32 v56, v56
	v_exp_f32_e32 v50, v50
	v_exp_f32_e32 v51, v51
	v_mul_f32_e32 v52, 0xba38aa3b, v52
	v_mul_f32_e32 v53, 0xba38aa3b, v53
	v_exp_f32_e32 v52, v52
	v_exp_f32_e32 v53, v53
	v_rcp_f32_e32 v0, v0
	v_rcp_f32_e32 v54, v54
	v_add_f32_e32 v55, 1.0, v55
	v_add_f32_e32 v56, 1.0, v56
	v_add_f32_e32 v50, 1.0, v50
	v_add_f32_e32 v51, 1.0, v51
	v_rcp_f32_e32 v55, v55
	v_rcp_f32_e32 v56, v56
	v_rcp_f32_e32 v50, v50
	v_rcp_f32_e32 v51, v51
	v_add_f32_e32 v52, 1.0, v52
	v_add_f32_e32 v53, 1.0, v53
	v_rcp_f32_e32 v52, v52
	v_rcp_f32_e32 v53, v53
	v_fma_f32 v0, v0, s49, 0.5
	v_fma_f32 v54, v54, s49, 0.5
	v_max_f32_e32 v0, 1.0, v0
	v_max_f32_e32 v54, 1.0, v54
	v_fma_f32 v55, v55, s49, 0.5
	v_fma_f32 v56, v56, s49, 0.5
	v_fma_f32 v50, v50, s49, 0.5
	v_fma_f32 v51, v51, s49, 0.5
	v_cvt_u32_f32_e32 v0, v0
	v_cvt_u32_f32_e32 v54, v54
	v_max_f32_e32 v55, 1.0, v55
	v_max_f32_e32 v56, 1.0, v56
	v_max_f32_e32 v50, 1.0, v50
	v_max_f32_e32 v51, 1.0, v51
	v_fma_f32 v52, v52, s49, 0.5
	v_fma_f32 v53, v53, s49, 0.5
	v_cvt_u32_f32_sdwa v55, v55 dst_sel:WORD_1 dst_unused:UNUSED_PAD src0_sel:DWORD
	v_cvt_u32_f32_sdwa v56, v56 dst_sel:BYTE_3 dst_unused:UNUSED_PAD src0_sel:DWORD
	v_cvt_u32_f32_e32 v50, v50
	v_cvt_u32_f32_e32 v51, v51
	v_max_f32_e32 v52, 1.0, v52
	v_max_f32_e32 v53, 1.0, v53
	v_cvt_u32_f32_sdwa v52, v52 dst_sel:WORD_1 dst_unused:UNUSED_PAD src0_sel:DWORD
	v_cvt_u32_f32_sdwa v53, v53 dst_sel:BYTE_3 dst_unused:UNUSED_PAD src0_sel:DWORD
	v_lshl_or_b32 v0, v54, 8, v0
	v_or3_b32 v60, v0, v55, v56
	v_lshl_or_b32 v0, v51, 8, v50
	v_or3_b32 v61, v0, v52, v53
	v_mul_f32_e32 v0, 0xba38aa3b, v46
	v_mul_f32_e32 v46, 0xba38aa3b, v47
	v_exp_f32_e32 v0, v0
	v_exp_f32_e32 v50, v46
	v_mul_f32_e32 v48, 0xba38aa3b, v48
	v_mul_f32_e32 v49, 0xba38aa3b, v49
	v_exp_f32_e32 v48, v48
	v_exp_f32_e32 v49, v49
	v_add_f32_e32 v0, 1.0, v0
	v_add_f32_e32 v50, 1.0, v50
	v_rcp_f32_e32 v0, v0
	v_rcp_f32_e32 v50, v50
	v_add_f32_e32 v48, 1.0, v48
	v_add_f32_e32 v49, 1.0, v49
	v_rcp_f32_e32 v48, v48
	v_rcp_f32_e32 v49, v49
	v_fma_f32 v0, v0, s49, 0.5
	v_fma_f32 v50, v50, s49, 0.5
	v_max_f32_e32 v0, 1.0, v0
	v_max_f32_e32 v50, 1.0, v50
	v_fma_f32 v48, v48, s49, 0.5
	v_fma_f32 v49, v49, s49, 0.5
	v_cvt_u32_f32_e32 v0, v0
	v_cvt_u32_f32_e32 v50, v50
	v_max_f32_e32 v48, 1.0, v48
	v_max_f32_e32 v49, 1.0, v49
	v_mul_f32_e32 v42, 0xba38aa3b, v42
	v_mul_f32_e32 v43, 0xba38aa3b, v43
	v_cvt_u32_f32_sdwa v48, v48 dst_sel:WORD_1 dst_unused:UNUSED_PAD src0_sel:DWORD
	v_cvt_u32_f32_sdwa v49, v49 dst_sel:BYTE_3 dst_unused:UNUSED_PAD src0_sel:DWORD
	v_exp_f32_e32 v51, v42
	v_exp_f32_e32 v43, v43
	v_lshl_or_b32 v0, v50, 8, v0
	v_or3_b32 v42, v0, v48, v49
	v_add_f32_e32 v0, 1.0, v51
	v_add_f32_e32 v43, 1.0, v43
	v_mul_f32_e32 v44, 0xba38aa3b, v44
	v_rcp_f32_e32 v0, v0
	v_rcp_f32_e32 v43, v43
	v_mul_f32_e32 v45, 0xba38aa3b, v45
	v_exp_f32_e32 v44, v44
	v_exp_f32_e32 v45, v45
	v_fma_f32 v0, v0, s49, 0.5
	v_fma_f32 v43, v43, s49, 0.5
	v_add_f32_e32 v44, 1.0, v44
	v_max_f32_e32 v0, 1.0, v0
	v_max_f32_e32 v43, 1.0, v43
	v_add_f32_e32 v45, 1.0, v45
	v_cvt_u32_f32_e32 v0, v0
	v_cvt_u32_f32_e32 v43, v43
	v_rcp_f32_e32 v44, v44
	v_rcp_f32_e32 v45, v45
	v_mul_f32_e32 v38, 0xba38aa3b, v38
	v_lshl_or_b32 v0, v43, 8, v0
	v_fma_f32 v43, v44, s49, 0.5
	v_fma_f32 v44, v45, s49, 0.5
	v_max_f32_e32 v43, 1.0, v43
	v_max_f32_e32 v44, 1.0, v44
	v_mul_f32_e32 v39, 0xba38aa3b, v39
	v_cvt_u32_f32_sdwa v43, v43 dst_sel:WORD_1 dst_unused:UNUSED_PAD src0_sel:DWORD
	v_cvt_u32_f32_sdwa v44, v44 dst_sel:BYTE_3 dst_unused:UNUSED_PAD src0_sel:DWORD
	v_exp_f32_e32 v38, v38
	v_exp_f32_e32 v39, v39
	v_mul_f32_e32 v34, 0xba38aa3b, v34
	v_or3_b32 v43, v0, v43, v44
	v_add_f32_e32 v0, 1.0, v38
	v_add_f32_e32 v38, 1.0, v39
	v_mul_f32_e32 v39, 0xba38aa3b, v40
	v_mul_f32_e32 v40, 0xba38aa3b, v41
	v_mul_f32_e32 v35, 0xba38aa3b, v35
	v_exp_f32_e32 v39, v39
	v_exp_f32_e32 v40, v40
	v_exp_f32_e32 v34, v34
	v_exp_f32_e32 v35, v35
	v_mul_f32_e32 v36, 0xba38aa3b, v36
	v_mul_f32_e32 v37, 0xba38aa3b, v37
	v_exp_f32_e32 v36, v36
	v_exp_f32_e32 v37, v37
	v_rcp_f32_e32 v0, v0
	v_rcp_f32_e32 v38, v38
	v_add_f32_e32 v39, 1.0, v39
	v_add_f32_e32 v40, 1.0, v40
	v_add_f32_e32 v34, 1.0, v34
	v_add_f32_e32 v35, 1.0, v35
	v_rcp_f32_e32 v39, v39
	v_rcp_f32_e32 v40, v40
	v_rcp_f32_e32 v34, v34
	v_rcp_f32_e32 v35, v35
	v_add_f32_e32 v36, 1.0, v36
	v_add_f32_e32 v37, 1.0, v37
	v_rcp_f32_e32 v36, v36
; #define GAS __attribute__((address_space(1)))
; __device__ __forceinline__ unsigned gate_q8(float g) { return (unsigned)fmaxf(g * 255.0f + 0.5f, 1.0f); }
; __device__ __forceinline__ unsigned gate_pk4(const f32x4& g) { return gate_q8(g[0]) | (gate_q8(g[1]) << 8) | (gate_q8(g[2]) << 16) | (gate_q8(g[3]) << 24); }
;     __device__ __forceinline__ void operator()(const f32x4 (&acc)[2][2][4][2], const pg8::GUnit& u, int wr, int wc, int fr, int fq) const {
;     ...
;         GAS unsigned char* gb = (GAS unsigned char*)P + (size_t)(u.pm * 256 + (wr * 4 + wc) * 32 + fq) * (INW * 2) + (GA * 2 + u.pn * 256 + fr * 16);
; #pragma unroll
;         for (int ai = 0; ai < 2; ++ai)
; #pragma unroll
;             for (int m = 0; m < 4; ++m) { u32x4 w; unsigned wq[4];
; #pragma unroll
;                 for (int bj = 0; bj < 2; ++bj)
; #pragma unroll
;                     for (int n = 0; n < 2; ++n) { f32x4 v = acc[ai][bj][m][n];
; #pragma unroll
;                         for (int j = 0; j < 4; ++j) v[j] = __builtin_amdgcn_rcpf(1.0f + __builtin_amdgcn_exp2f(v[j] * (-LOG2E * G8_DESCALE)));
;                         wq[bj * 2 + n] = gate_pk4(v); }
;                 w.x = wq[0]; w.y = wq[1]; w.z = wq[2]; w.w = wq[3];
;                 *(GAS u32x4*)(gb + (size_t)((ai * 4 + m) * 4) * (INW * 2)) = w; }
	v_rcp_f32_e32 v37, v37
	v_fma_f32 v0, v0, s49, 0.5
	v_fma_f32 v38, v38, s49, 0.5
	v_max_f32_e32 v0, 1.0, v0
	v_max_f32_e32 v38, 1.0, v38
	v_fma_f32 v39, v39, s49, 0.5
	v_fma_f32 v40, v40, s49, 0.5
	v_fma_f32 v34, v34, s49, 0.5
	v_fma_f32 v35, v35, s49, 0.5
	v_cvt_u32_f32_e32 v0, v0
	v_cvt_u32_f32_e32 v38, v38
	v_max_f32_e32 v39, 1.0, v39
	v_max_f32_e32 v40, 1.0, v40
	v_max_f32_e32 v34, 1.0, v34
	v_max_f32_e32 v35, 1.0, v35
	v_fma_f32 v36, v36, s49, 0.5
	v_fma_f32 v37, v37, s49, 0.5
	v_cvt_u32_f32_sdwa v39, v39 dst_sel:WORD_1 dst_unused:UNUSED_PAD src0_sel:DWORD
	v_cvt_u32_f32_sdwa v40, v40 dst_sel:BYTE_3 dst_unused:UNUSED_PAD src0_sel:DWORD
	v_cvt_u32_f32_e32 v34, v34
	v_cvt_u32_f32_e32 v35, v35
	v_max_f32_e32 v36, 1.0, v36
	v_max_f32_e32 v37, 1.0, v37
	v_cvt_u32_f32_sdwa v36, v36 dst_sel:WORD_1 dst_unused:UNUSED_PAD src0_sel:DWORD
	v_cvt_u32_f32_sdwa v37, v37 dst_sel:BYTE_3 dst_unused:UNUSED_PAD src0_sel:DWORD
	v_lshl_or_b32 v0, v38, 8, v0
	v_or3_b32 v44, v0, v39, v40
	v_lshl_or_b32 v0, v35, 8, v34
	v_or3_b32 v45, v0, v36, v37
	v_mul_f32_e32 v0, 0xba38aa3b, v30
	v_mul_f32_e32 v30, 0xba38aa3b, v31
	v_exp_f32_e32 v0, v0
	v_exp_f32_e32 v34, v30
	v_mul_f32_e32 v32, 0xba38aa3b, v32
	v_mul_f32_e32 v33, 0xba38aa3b, v33
	v_exp_f32_e32 v32, v32
	v_exp_f32_e32 v33, v33
	v_add_f32_e32 v0, 1.0, v0
	v_add_f32_e32 v34, 1.0, v34
	v_rcp_f32_e32 v0, v0
	v_rcp_f32_e32 v34, v34
	v_add_f32_e32 v32, 1.0, v32
	v_add_f32_e32 v33, 1.0, v33
	v_rcp_f32_e32 v32, v32
	v_rcp_f32_e32 v33, v33
	v_fma_f32 v0, v0, s49, 0.5
	v_fma_f32 v34, v34, s49, 0.5
	v_max_f32_e32 v0, 1.0, v0
	v_max_f32_e32 v34, 1.0, v34
	v_fma_f32 v32, v32, s49, 0.5
	v_fma_f32 v33, v33, s49, 0.5
	v_cvt_u32_f32_e32 v0, v0
	v_cvt_u32_f32_e32 v34, v34
	v_max_f32_e32 v32, 1.0, v32
	v_max_f32_e32 v33, 1.0, v33
	v_mul_f32_e32 v26, 0xba38aa3b, v26
	v_mul_f32_e32 v27, 0xba38aa3b, v27
	v_cvt_u32_f32_sdwa v32, v32 dst_sel:WORD_1 dst_unused:UNUSED_PAD src0_sel:DWORD
	v_cvt_u32_f32_sdwa v33, v33 dst_sel:BYTE_3 dst_unused:UNUSED_PAD src0_sel:DWORD
	v_exp_f32_e32 v35, v26
	v_exp_f32_e32 v27, v27
	v_lshl_or_b32 v0, v34, 8, v0
	v_or3_b32 v26, v0, v32, v33
	v_add_f32_e32 v0, 1.0, v35
	v_add_f32_e32 v27, 1.0, v27
	v_mul_f32_e32 v28, 0xba38aa3b, v28
	v_rcp_f32_e32 v0, v0
	v_rcp_f32_e32 v27, v27
	v_mul_f32_e32 v29, 0xba38aa3b, v29
	v_exp_f32_e32 v28, v28
	v_exp_f32_e32 v29, v29
	v_fma_f32 v0, v0, s49, 0.5
	v_fma_f32 v27, v27, s49, 0.5
	v_add_f32_e32 v28, 1.0, v28
	v_max_f32_e32 v0, 1.0, v0
	v_max_f32_e32 v27, 1.0, v27
	v_add_f32_e32 v29, 1.0, v29
	v_cvt_u32_f32_e32 v0, v0
	v_cvt_u32_f32_e32 v27, v27
	v_rcp_f32_e32 v28, v28
	v_rcp_f32_e32 v29, v29
	v_mul_f32_e32 v22, 0xba38aa3b, v22
	v_lshl_or_b32 v0, v27, 8, v0
	v_fma_f32 v27, v28, s49, 0.5
	v_fma_f32 v28, v29, s49, 0.5
	v_max_f32_e32 v27, 1.0, v27
	v_max_f32_e32 v28, 1.0, v28
	v_mul_f32_e32 v23, 0xba38aa3b, v23
	v_cvt_u32_f32_sdwa v27, v27 dst_sel:WORD_1 dst_unused:UNUSED_PAD src0_sel:DWORD
	v_cvt_u32_f32_sdwa v28, v28 dst_sel:BYTE_3 dst_unused:UNUSED_PAD src0_sel:DWORD
	v_exp_f32_e32 v22, v22
	v_exp_f32_e32 v23, v23
	v_mul_f32_e32 v18, 0xba38aa3b, v18
	v_or3_b32 v27, v0, v27, v28
	v_add_f32_e32 v0, 1.0, v22
	v_add_f32_e32 v22, 1.0, v23
	v_mul_f32_e32 v23, 0xba38aa3b, v24
	v_mul_f32_e32 v24, 0xba38aa3b, v25
	v_mul_f32_e32 v19, 0xba38aa3b, v19
	v_exp_f32_e32 v23, v23
	v_exp_f32_e32 v24, v24
	v_exp_f32_e32 v18, v18
	v_exp_f32_e32 v19, v19
	v_mul_f32_e32 v20, 0xba38aa3b, v20
	v_mul_f32_e32 v21, 0xba38aa3b, v21
	v_exp_f32_e32 v20, v20
	v_exp_f32_e32 v21, v21
	v_rcp_f32_e32 v0, v0
	v_rcp_f32_e32 v22, v22
	v_add_f32_e32 v23, 1.0, v23
	v_add_f32_e32 v24, 1.0, v24
	v_add_f32_e32 v18, 1.0, v18
	v_add_f32_e32 v19, 1.0, v19
	v_rcp_f32_e32 v23, v23
	v_rcp_f32_e32 v24, v24
	v_rcp_f32_e32 v18, v18
	v_rcp_f32_e32 v19, v19
	v_add_f32_e32 v20, 1.0, v20
	v_add_f32_e32 v21, 1.0, v21
	v_rcp_f32_e32 v20, v20
	v_rcp_f32_e32 v21, v21
	v_fma_f32 v0, v0, s49, 0.5
	v_fma_f32 v22, v22, s49, 0.5
	v_max_f32_e32 v0, 1.0, v0
	v_max_f32_e32 v22, 1.0, v22
	v_fma_f32 v23, v23, s49, 0.5
	v_fma_f32 v24, v24, s49, 0.5
	v_fma_f32 v18, v18, s49, 0.5
	v_fma_f32 v19, v19, s49, 0.5
	v_cvt_u32_f32_e32 v0, v0
	v_cvt_u32_f32_e32 v22, v22
	v_max_f32_e32 v23, 1.0, v23
	v_max_f32_e32 v24, 1.0, v24
	v_max_f32_e32 v18, 1.0, v18
	v_max_f32_e32 v19, 1.0, v19
	v_fma_f32 v20, v20, s49, 0.5
	v_fma_f32 v21, v21, s49, 0.5
	v_cvt_u32_f32_sdwa v23, v23 dst_sel:WORD_1 dst_unused:UNUSED_PAD src0_sel:DWORD
	v_cvt_u32_f32_sdwa v24, v24 dst_sel:BYTE_3 dst_unused:UNUSED_PAD src0_sel:DWORD
	v_cvt_u32_f32_e32 v18, v18
	v_cvt_u32_f32_e32 v19, v19
	v_max_f32_e32 v20, 1.0, v20
	v_max_f32_e32 v21, 1.0, v21
	v_cvt_u32_f32_sdwa v20, v20 dst_sel:WORD_1 dst_unused:UNUSED_PAD src0_sel:DWORD
	v_cvt_u32_f32_sdwa v21, v21 dst_sel:BYTE_3 dst_unused:UNUSED_PAD src0_sel:DWORD
	v_lshl_or_b32 v0, v22, 8, v0
	v_or3_b32 v28, v0, v23, v24
	v_lshl_or_b32 v0, v19, 8, v18
	v_or3_b32 v29, v0, v20, v21
	v_mul_f32_e32 v0, 0xba38aa3b, v14
	v_mul_f32_e32 v14, 0xba38aa3b, v15
	v_exp_f32_e32 v0, v0
	v_exp_f32_e32 v18, v14
; #define GAS __attribute__((address_space(1)))
; __device__ __forceinline__ int lane_id_hw() { int l; asm volatile("v_mbcnt_lo_u32_b32 %0, -1, 0\n\tv_mbcnt_hi_u32_b32 %0, -1, %0" : "=v"(l)); return l; }
; __device__ __forceinline__ unsigned gate_pk4(const f32x4& g) { return gate_q8(g[0]) | (gate_q8(g[1]) << 8) | (gate_q8(g[2]) << 16) | (gate_q8(g[3]) << 24); }
;     ...
;         { const int l2 = lane_id_hw(); E(acc, cur, wr, wc, l2 & 15, l2 >> 4); }
;         if (!has_next) break;
;     __device__ __forceinline__ void operator()(const f32x4 (&acc)[2][2][4][2], const pg8::GUnit& u, int wr, int wc, int fr, int fq) const {
;     ...
;             for (int m = 0; m < 4; ++m) { u32x4 w; unsigned wq[4];
; #pragma unroll
;                 for (int bj = 0; bj < 2; ++bj)
; #pragma unroll
;                     for (int n = 0; n < 2; ++n) { f32x4 v = acc[ai][bj][m][n];
; #pragma unroll
;                         for (int j = 0; j < 4; ++j) v[j] = __builtin_amdgcn_rcpf(1.0f + __builtin_amdgcn_exp2f(v[j] * (-LOG2E * G8_DESCALE)));
;                         wq[bj * 2 + n] = gate_pk4(v); }
;                 w.x = wq[0]; w.y = wq[1]; w.z = wq[2]; w.w = wq[3];
;                 *(GAS u32x4*)(gb + (size_t)((ai * 4 + m) * 4) * (INW * 2)) = w; }
	v_mul_f32_e32 v16, 0xba38aa3b, v16
	v_mul_f32_e32 v17, 0xba38aa3b, v17
	v_exp_f32_e32 v16, v16
	v_exp_f32_e32 v17, v17
	v_add_f32_e32 v0, 1.0, v0
	v_add_f32_e32 v18, 1.0, v18
	v_rcp_f32_e32 v0, v0
	v_rcp_f32_e32 v18, v18
	v_add_f32_e32 v16, 1.0, v16
	v_add_f32_e32 v17, 1.0, v17
	v_rcp_f32_e32 v16, v16
	v_rcp_f32_e32 v17, v17
	v_fma_f32 v0, v0, s49, 0.5
	v_fma_f32 v18, v18, s49, 0.5
	v_max_f32_e32 v0, 1.0, v0
	v_max_f32_e32 v18, 1.0, v18
	v_fma_f32 v16, v16, s49, 0.5
	v_fma_f32 v17, v17, s49, 0.5
	v_cvt_u32_f32_e32 v0, v0
	v_cvt_u32_f32_e32 v18, v18
	v_max_f32_e32 v16, 1.0, v16
	v_max_f32_e32 v17, 1.0, v17
	v_mul_f32_e32 v10, 0xba38aa3b, v10
	v_mul_f32_e32 v11, 0xba38aa3b, v11
	v_cvt_u32_f32_sdwa v16, v16 dst_sel:WORD_1 dst_unused:UNUSED_PAD src0_sel:DWORD
	v_cvt_u32_f32_sdwa v17, v17 dst_sel:BYTE_3 dst_unused:UNUSED_PAD src0_sel:DWORD
	v_exp_f32_e32 v19, v10
	v_exp_f32_e32 v11, v11
	v_lshl_or_b32 v0, v18, 8, v0
	v_or3_b32 v10, v0, v16, v17
	v_add_f32_e32 v0, 1.0, v19
	v_add_f32_e32 v11, 1.0, v11
	v_mul_f32_e32 v12, 0xba38aa3b, v12
	v_rcp_f32_e32 v0, v0
	v_rcp_f32_e32 v11, v11
	v_mul_f32_e32 v13, 0xba38aa3b, v13
	v_exp_f32_e32 v12, v12
	v_exp_f32_e32 v13, v13
	v_fma_f32 v0, v0, s49, 0.5
	v_fma_f32 v11, v11, s49, 0.5
	v_add_f32_e32 v12, 1.0, v12
	v_max_f32_e32 v0, 1.0, v0
	v_max_f32_e32 v11, 1.0, v11
	v_add_f32_e32 v13, 1.0, v13
	v_cvt_u32_f32_e32 v0, v0
	v_cvt_u32_f32_e32 v11, v11
	v_rcp_f32_e32 v12, v12
	v_rcp_f32_e32 v13, v13
	v_mul_f32_e32 v6, 0xba38aa3b, v6
	v_lshl_or_b32 v0, v11, 8, v0
	v_fma_f32 v11, v12, s49, 0.5
	v_fma_f32 v12, v13, s49, 0.5
	v_max_f32_e32 v11, 1.0, v11
	v_max_f32_e32 v12, 1.0, v12
	v_mul_f32_e32 v7, 0xba38aa3b, v7
	v_cvt_u32_f32_sdwa v11, v11 dst_sel:WORD_1 dst_unused:UNUSED_PAD src0_sel:DWORD
	v_cvt_u32_f32_sdwa v12, v12 dst_sel:BYTE_3 dst_unused:UNUSED_PAD src0_sel:DWORD
	v_exp_f32_e32 v6, v6
	v_exp_f32_e32 v7, v7
	s_lshl_b32 s39, s39, 8
	s_add_i32 s39, s40, s39
	v_or3_b32 v11, v0, v11, v12
	v_add_f32_e32 v0, 1.0, v6
	v_add_f32_e32 v6, 1.0, v7
	v_mul_f32_e32 v7, 0xba38aa3b, v8
	v_mul_f32_e32 v8, 0xba38aa3b, v9
	v_mul_f32_e32 v2, 0xba38aa3b, v2
	v_mul_f32_e32 v3, 0xba38aa3b, v3
	v_add_u32_e32 v140, s39, v140
	v_exp_f32_e32 v7, v7
	v_exp_f32_e32 v8, v8
	v_exp_f32_e32 v2, v2
	v_exp_f32_e32 v3, v3
	v_mad_i64_i32 v[140:141], s[44:45], v140, s93, v[132:133]
	v_ashrrev_i32_e32 v143, 31, v142
	v_mul_f32_e32 v4, 0xba38aa3b, v4
	v_mul_f32_e32 v5, 0xba38aa3b, v5
	v_lshl_add_u64 v[126:127], v[140:141], 0, v[142:143]
	v_exp_f32_e32 v4, v4
	v_exp_f32_e32 v5, v5
	v_add_co_u32_e32 v94, vcc, s48, v126
	v_rcp_f32_e32 v0, v0
	s_nop 0
	v_addc_co_u32_e32 v95, vcc, 0, v127, vcc
	v_rcp_f32_e32 v6, v6
	v_add_f32_e32 v7, 1.0, v7
	v_add_f32_e32 v8, 1.0, v8
	v_add_f32_e32 v2, 1.0, v2
	v_add_f32_e32 v3, 1.0, v3
	v_add_co_u32_e32 v78, vcc, s26, v126
	v_rcp_f32_e32 v7, v7
	v_rcp_f32_e32 v8, v8
	v_rcp_f32_e32 v2, v2
	v_rcp_f32_e32 v3, v3
	v_addc_co_u32_e32 v79, vcc, 0, v127, vcc
	s_mov_b32 s38, 0x90000
	v_add_f32_e32 v4, 1.0, v4
	v_add_f32_e32 v5, 1.0, v5
	v_add_co_u32_e32 v62, vcc, s38, v126
	v_rcp_f32_e32 v4, v4
	v_rcp_f32_e32 v5, v5
	v_addc_co_u32_e32 v63, vcc, 0, v127, vcc
	s_mov_b32 s38, 0xc0000
	v_fma_f32 v0, v0, s49, 0.5
	v_fma_f32 v6, v6, s49, 0.5
	v_add_co_u32_e32 v46, vcc, s38, v126
	v_max_f32_e32 v0, 1.0, v0
	v_max_f32_e32 v6, 1.0, v6
	v_fma_f32 v7, v7, s49, 0.5
	v_fma_f32 v8, v8, s49, 0.5
	v_fma_f32 v2, v2, s49, 0.5
	v_fma_f32 v3, v3, s49, 0.5
	v_addc_co_u32_e32 v47, vcc, 0, v127, vcc
	s_mov_b32 s38, 0xf0000
	v_cvt_u32_f32_e32 v0, v0
	v_cvt_u32_f32_e32 v6, v6
	v_max_f32_e32 v7, 1.0, v7
	v_max_f32_e32 v8, 1.0, v8
	v_max_f32_e32 v2, 1.0, v2
	v_max_f32_e32 v3, 1.0, v3
	v_add_co_u32_e32 v30, vcc, s38, v126
	v_cvt_u32_f32_sdwa v7, v7 dst_sel:WORD_1 dst_unused:UNUSED_PAD src0_sel:DWORD
	v_cvt_u32_f32_sdwa v8, v8 dst_sel:BYTE_3 dst_unused:UNUSED_PAD src0_sel:DWORD
	v_cvt_u32_f32_e32 v2, v2
	v_cvt_u32_f32_e32 v3, v3
	v_fma_f32 v4, v4, s49, 0.5
	v_fma_f32 v5, v5, s49, 0.5
	v_addc_co_u32_e32 v31, vcc, 0, v127, vcc
	v_max_f32_e32 v4, 1.0, v4
	v_max_f32_e32 v5, 1.0, v5
	v_add_co_u32_e32 v14, vcc, s27, v126
	v_cvt_u32_f32_sdwa v4, v4 dst_sel:WORD_1 dst_unused:UNUSED_PAD src0_sel:DWORD
	v_cvt_u32_f32_sdwa v5, v5 dst_sel:BYTE_3 dst_unused:UNUSED_PAD src0_sel:DWORD
	v_addc_co_u32_e32 v15, vcc, 0, v127, vcc
	v_lshl_or_b32 v0, v6, 8, v0
	v_or3_b32 v12, v0, v7, v8
	v_lshl_or_b32 v0, v3, 8, v2
	v_add_co_u32_e32 v2, vcc, 0x150000, v126
	v_or3_b32 v13, v0, v4, v5
	s_nop 0
	v_addc_co_u32_e32 v3, vcc, 0, v127, vcc
	s_and_b64 vcc, exec, s[4:5]
	s_mov_b32 s39, s25
	s_mov_b32 s38, s24
	s_mov_b32 s45, s37
	s_mov_b32 s44, s36
	global_store_dwordx4 v[126:127], v[122:125], off
	global_store_dwordx4 v[94:95], v[106:109], off
	global_store_dwordx4 v[78:79], v[90:93], off
	global_store_dwordx4 v[62:63], v[74:77], off
	global_store_dwordx4 v[46:47], v[58:61], off
	global_store_dwordx4 v[30:31], v[42:45], off
	global_store_dwordx4 v[14:15], v[26:29], off
	global_store_dwordx4 v[2:3], v[10:13], off
	s_cbranch_vccnz .Lf8_phase_end

; #define PG8_STAGE(bufoff, gbase, voff) do { unsigned _g = (gbase); asm volatile("" : "+s"(_g));   _Pragma("unroll") for (int _i = 0; _i < 2; ++_i) \
;         __builtin_amdgcn_global_load_lds((const unsigned*)(wsb + (size_t)(unsigned)(_g + (voff)[_i])), (LAS unsigned*)(lds + (bufoff) + ldsw + _i * 8192), 16, 0, 0); } while (0)
; #define PG8_WAIT_V(n) asm volatile("s_waitcnt vmcnt(" #n ")" ::: "memory")
; #define PG8_WAIT_L(n) asm volatile("s_waitcnt lgkmcnt(" #n ")" ::: "memory")
; #define PG8_BAR __builtin_amdgcn_s_barrier()
; #define PG8_SCHED __builtin_amdgcn_sched_barrier(0)
;     ...
;             PG8_LDB(B0, 0, 0); PG8_LDB(B1, 0, 1); PG8_SCHED; PG8_LDA(At, 0, 0); PG8_STAGE(PG8_SA(1, 1), a1 + hstep, voffA);
;             PG8_WAIT_V(8); PG8_WAIT_L(0); PG8_BAR; PG8_MMA(0, 0, At, B0); PG8_MMA(0, 1, At, B1); PG8_BAR; PG8_SCHED;
;             PG8_LDA(At, 0, 1); PG8_STAGE(PG8_SB(0, 0), b2, voffB); PG8_STAGE(PG8_SB(0, 1), b2 + hstep, voffB); PG8_STAGE(PG8_SA(0, 0), a2, voffA);
;             PG8_WAIT_V(8); PG8_WAIT_L(0); PG8_BAR; PG8_MMA(1, 0, At, B0); PG8_MMA(1, 1, At, B1); PG8_BAR; PG8_SCHED;
.Lf8_iter_peel:
	s_add_i32 s47, s44, 0xfff80080
	s_cmp_eq_u32 s46, 28
	s_cselect_b32 s83, s36, s47
	s_cselect_b32 s47, s37, s45
	s_add_i32 s84, 0, 0x10000
	v_add_u32_e32 v0, s84, v138
	s_add_i32 s86, 0, 0x14000
	ds_read_b128 v[140:143], v0
	ds_read_b128 v[144:147], v0 offset:1024
	ds_read_b128 v[148:151], v0 offset:2048
	ds_read_b128 v[152:155], v0 offset:3072
	v_add_u32_e32 v0, s86, v138
	ds_read_b128 v[156:159], v0
	ds_read_b128 v[160:163], v0 offset:1024
	ds_read_b128 v[164:167], v0 offset:2048
	ds_read_b128 v[168:171], v0 offset:3072
	s_add_i32 s82, s83, 0x80
	s_mov_b32 s87, s44
	ds_read_b128 v[172:175], v139
	ds_read_b128 v[176:179], v139 offset:1024
	ds_read_b128 v[180:183], v139 offset:2048
	ds_read_b128 v[184:187], v139 offset:3072
	ds_read_b128 v[188:191], v139 offset:4096
	ds_read_b128 v[192:195], v139 offset:5120
	ds_read_b128 v[196:199], v139 offset:6144
	ds_read_b128 v[200:203], v139 offset:7168
	s_add_i32 m0, s9, 0xc000
	v_add_u32_e32 v0, s87, v134
	v_lshl_add_u64 v[204:205], v[130:131], 0, v[0:1]
	v_add_u32_e32 v0, s87, v136
	global_load_lds_dwordx4 v[204:205], off
	v_lshl_add_u64 v[204:205], v[130:131], 0, v[0:1]
	s_add_i32 m0, s9, 0xe000
	s_nop 0
	global_load_lds_dwordx4 v[204:205], off
	s_waitcnt vmcnt(16)
	s_waitcnt lgkmcnt(0)
	s_barrier
	s_setprio 1
	s_waitcnt lgkmcnt(0)
	v_mfma_f32_16x16x128_f8f6f4 v[126:129], v[140:147], v[172:179], v[126:129]
	v_mfma_f32_16x16x128_f8f6f4 v[122:125], v[148:155], v[172:179], v[122:125]
	v_mfma_f32_16x16x128_f8f6f4 v[110:113], v[140:147], v[180:187], v[110:113]
	v_mfma_f32_16x16x128_f8f6f4 v[106:109], v[148:155], v[180:187], v[106:109]
	v_mfma_f32_16x16x128_f8f6f4 v[204:207], v[140:147], v[188:195], v[94:97]
	v_mfma_f32_16x16x128_f8f6f4 v[208:211], v[148:155], v[188:195], v[90:93]
	v_mfma_f32_16x16x128_f8f6f4 v[212:215], v[140:147], v[196:203], v[78:81]
	v_mfma_f32_16x16x128_f8f6f4 v[216:219], v[148:155], v[196:203], v[74:77]
	s_setprio 0
	s_setprio 1
	v_mfma_f32_16x16x128_f8f6f4 v[118:121], v[156:163], v[172:179], v[118:121]
	v_mfma_f32_16x16x128_f8f6f4 v[114:117], v[164:171], v[172:179], v[114:117]
	v_mfma_f32_16x16x128_f8f6f4 v[102:105], v[156:163], v[180:187], v[102:105]
	v_mfma_f32_16x16x128_f8f6f4 v[98:101], v[164:171], v[180:187], v[98:101]
	v_mfma_f32_16x16x128_f8f6f4 v[172:175], v[156:163], v[188:195], v[86:89]
	v_mfma_f32_16x16x128_f8f6f4 v[176:179], v[164:171], v[188:195], v[82:85]
	v_mfma_f32_16x16x128_f8f6f4 v[180:183], v[156:163], v[196:203], v[70:73]
	v_mfma_f32_16x16x128_f8f6f4 v[184:187], v[164:171], v[196:203], v[66:69]
	s_setprio 0
	s_barrier
	s_mov_b32 s87, s47
	s_nop 3
	ds_read_b128 v[66:69], v139 offset:16384
	ds_read_b128 v[70:73], v139 offset:17408
	ds_read_b128 v[74:77], v139 offset:18432
	ds_read_b128 v[78:81], v139 offset:19456
	ds_read_b128 v[82:85], v139 offset:20480
	ds_read_b128 v[86:89], v139 offset:21504
	ds_read_b128 v[90:93], v139 offset:22528
	ds_read_b128 v[94:97], v139 offset:23552
	s_add_i32 s84, s84, s7
	v_add_u32_e32 v0, s87, v135
	v_lshl_add_u64 v[188:189], v[130:131], 0, v[0:1]
	s_mov_b32 m0, s84
	v_add_u32_e32 v0, s87, v137
	global_load_lds_dwordx4 v[188:189], off
	v_lshl_add_u64 v[188:189], v[130:131], 0, v[0:1]
	s_add_i32 m0, s84, 0x2000
	s_add_i32 s84, s47, 0x80000
	global_load_lds_dwordx4 v[188:189], off
	s_add_i32 s86, s86, s7
	v_add_u32_e32 v0, s84, v135
	v_lshl_add_u64 v[188:189], v[130:131], 0, v[0:1]
	s_mov_b32 m0, s86
	v_add_u32_e32 v0, s84, v137
	global_load_lds_dwordx4 v[188:189], off
	v_lshl_add_u64 v[188:189], v[130:131], 0, v[0:1]
	s_add_i32 m0, s86, 0x2000
	s_mov_b32 s84, s83
	global_load_lds_dwordx4 v[188:189], off
	s_mov_b32 m0, s9
	v_add_u32_e32 v0, s84, v134
	v_lshl_add_u64 v[188:189], v[130:131], 0, v[0:1]
	v_add_u32_e32 v0, s84, v136
	global_load_lds_dwordx4 v[188:189], off
	v_lshl_add_u64 v[188:189], v[130:131], 0, v[0:1]
	s_mov_b32 m0, s11
	s_nop 0
	global_load_lds_dwordx4 v[188:189], off
	s_waitcnt vmcnt(16)
	s_waitcnt lgkmcnt(0)
	s_barrier
	s_setprio 1
	s_waitcnt lgkmcnt(0)
	v_mfma_f32_16x16x128_f8f6f4 v[62:65], v[140:147], v[66:73], v[62:65]
	v_mfma_f32_16x16x128_f8f6f4 v[58:61], v[148:155], v[66:73], v[58:61]
	v_mfma_f32_16x16x128_f8f6f4 v[188:191], v[140:147], v[74:81], v[46:49]
	v_mfma_f32_16x16x128_f8f6f4 v[192:195], v[148:155], v[74:81], v[42:45]
	v_mfma_f32_16x16x128_f8f6f4 v[196:199], v[140:147], v[82:89], v[30:33]
	v_mfma_f32_16x16x128_f8f6f4 v[200:203], v[148:155], v[82:89], v[26:29]
	v_mfma_f32_16x16x128_f8f6f4 v[220:223], v[140:147], v[90:97], v[14:17]
	v_mfma_f32_16x16x128_f8f6f4 v[224:227], v[148:155], v[90:97], v[10:13]
	s_setprio 0
	s_setprio 1
	v_mfma_f32_16x16x128_f8f6f4 v[54:57], v[156:163], v[66:73], v[54:57]
	v_mfma_f32_16x16x128_f8f6f4 v[50:53], v[164:171], v[66:73], v[50:53]
	v_mfma_f32_16x16x128_f8f6f4 v[228:231], v[156:163], v[74:81], v[38:41]
	v_mfma_f32_16x16x128_f8f6f4 v[232:235], v[164:171], v[74:81], v[34:37]
	v_mfma_f32_16x16x128_f8f6f4 v[236:239], v[156:163], v[82:89], v[22:25]
	v_mfma_f32_16x16x128_f8f6f4 v[246:249], v[164:171], v[82:89], v[18:21]
	v_mfma_f32_16x16x128_f8f6f4 v[250:253], v[156:163], v[90:97], v[6:9]
	v_mfma_f32_16x16x128_f8f6f4 v[240:243], v[164:171], v[90:97], v[2:5]
	s_setprio 0
	s_barrier
; #define PG8_STAGE(bufoff, gbase, voff) do { unsigned _g = (gbase); asm volatile("" : "+s"(_g));   _Pragma("unroll") for (int _i = 0; _i < 2; ++_i) \
;         __builtin_amdgcn_global_load_lds((const unsigned*)(wsb + (size_t)(unsigned)(_g + (voff)[_i])), (LAS unsigned*)(lds + (bufoff) + ldsw + _i * 8192), 16, 0, 0); } while (0)
; #define PG8_WAIT_V(n) asm volatile("s_waitcnt vmcnt(" #n ")" ::: "memory")
; #define PG8_WAIT_L(n) asm volatile("s_waitcnt lgkmcnt(" #n ")" ::: "memory")
; #define PG8_BAR __builtin_amdgcn_s_barrier()
; #define PG8_SCHED __builtin_amdgcn_sched_barrier(0)
;     ...
;             PG8_LDB(B0, 1, 0); PG8_LDB(B1, 1, 1); PG8_SCHED; PG8_LDA(At, 1, 0); PG8_STAGE(PG8_SA(0, 1), a2 + hstep, voffA);
;             PG8_WAIT_V(8); PG8_WAIT_L(0); PG8_BAR; PG8_MMA(0, 0, At, B0); PG8_MMA(0, 1, At, B1); PG8_BAR; PG8_SCHED;
;             PG8_LDA(At, 1, 1); PG8_STAGE(PG8_SB(1, 0), b3, voffB); PG8_STAGE(PG8_SB(1, 1), b3 + hstep, voffB); PG8_STAGE(PG8_SA(1, 0), a3, voffA);
;             PG8_WAIT_V(8); PG8_WAIT_L(0); PG8_BAR; PG8_MMA(1, 0, At, B0); PG8_MMA(1, 1, At, B1); PG8_BAR; PG8_SCHED;
;     ...
;     PG8_WAIT_V(0);
;     if (wr == 0) PG8_BAR;
;     PG8_BAR;
	s_add_i32 s84, 0, 0x18000
	v_add_u32_e32 v0, s84, v138
	s_add_i32 s86, 0, 0x1c000
	s_nop 1
	ds_read_b128 v[2:5], v0
	ds_read_b128 v[6:9], v0 offset:1024
	ds_read_b128 v[18:21], v0 offset:2048
	ds_read_b128 v[22:25], v0 offset:3072
	v_add_u32_e32 v0, s86, v138
	ds_read_b128 v[140:143], v0
	ds_read_b128 v[144:147], v0 offset:1024
	ds_read_b128 v[148:151], v0 offset:2048
	ds_read_b128 v[152:155], v0 offset:3072
	s_add_i32 s83, s83, 0x80000
	ds_read_b128 v[10:13], v139 offset:32768
	ds_read_b128 v[14:17], v139 offset:33792
	ds_read_b128 v[26:29], v139 offset:34816
	ds_read_b128 v[30:33], v139 offset:35840
	ds_read_b128 v[34:37], v139 offset:36864
	ds_read_b128 v[38:41], v139 offset:37888
	ds_read_b128 v[42:45], v139 offset:38912
	ds_read_b128 v[46:49], v139 offset:39936
	s_mov_b32 m0, s12
	v_add_u32_e32 v0, s83, v134
	v_lshl_add_u64 v[66:67], v[130:131], 0, v[0:1]
	v_add_u32_e32 v0, s83, v136
	global_load_lds_dwordx4 v[66:67], off
	v_lshl_add_u64 v[66:67], v[130:131], 0, v[0:1]
	s_mov_b32 m0, s13
	s_nop 0
	global_load_lds_dwordx4 v[66:67], off
	s_waitcnt vmcnt(8)
	s_waitcnt lgkmcnt(0)
	s_barrier
	s_setprio 1
	s_waitcnt lgkmcnt(0)
	v_mfma_f32_16x16x128_f8f6f4 v[126:129], v[2:9], v[10:17], v[126:129]
	v_mfma_f32_16x16x128_f8f6f4 v[122:125], v[18:25], v[10:17], v[122:125]
	v_mfma_f32_16x16x128_f8f6f4 v[110:113], v[2:9], v[26:33], v[110:113]
	v_mfma_f32_16x16x128_f8f6f4 v[106:109], v[18:25], v[26:33], v[106:109]
	v_mfma_f32_16x16x128_f8f6f4 v[94:97], v[2:9], v[34:41], v[204:207]
	v_mfma_f32_16x16x128_f8f6f4 v[90:93], v[18:25], v[34:41], v[208:211]
	v_mfma_f32_16x16x128_f8f6f4 v[78:81], v[2:9], v[42:49], v[212:215]
	v_mfma_f32_16x16x128_f8f6f4 v[74:77], v[18:25], v[42:49], v[216:219]
	s_setprio 0
	s_setprio 1
	v_mfma_f32_16x16x128_f8f6f4 v[118:121], v[140:147], v[10:17], v[118:121]
	v_mfma_f32_16x16x128_f8f6f4 v[114:117], v[148:155], v[10:17], v[114:117]
	v_mfma_f32_16x16x128_f8f6f4 v[102:105], v[140:147], v[26:33], v[102:105]
	v_mfma_f32_16x16x128_f8f6f4 v[98:101], v[148:155], v[26:33], v[98:101]
	v_mfma_f32_16x16x128_f8f6f4 v[86:89], v[140:147], v[34:41], v[172:175]
	v_mfma_f32_16x16x128_f8f6f4 v[82:85], v[148:155], v[34:41], v[176:179]
	v_mfma_f32_16x16x128_f8f6f4 v[70:73], v[140:147], v[42:49], v[180:183]
	v_mfma_f32_16x16x128_f8f6f4 v[66:69], v[148:155], v[42:49], v[184:187]
	s_setprio 0
	s_barrier
	s_add_i32 s83, s47, 0x80
	ds_read_b128 v[34:37], v139 offset:49152
	ds_read_b128 v[38:41], v139 offset:50176
	ds_read_b128 v[156:159], v139 offset:51200
	ds_read_b128 v[160:163], v139 offset:52224
	ds_read_b128 v[164:167], v139 offset:53248
	ds_read_b128 v[168:171], v139 offset:54272
	ds_read_b128 v[172:175], v139 offset:55296
	ds_read_b128 v[176:179], v139 offset:56320
	s_add_i32 s84, s84, s7
	v_add_u32_e32 v0, s83, v135
	v_lshl_add_u64 v[10:11], v[130:131], 0, v[0:1]
	s_mov_b32 m0, s84
	v_add_u32_e32 v0, s83, v137
	global_load_lds_dwordx4 v[10:11], off
	v_lshl_add_u64 v[10:11], v[130:131], 0, v[0:1]
	s_add_i32 m0, s84, 0x2000
	s_add_i32 s47, s47, 0x80080
	global_load_lds_dwordx4 v[10:11], off
	s_add_i32 s83, s86, s7
	v_add_u32_e32 v0, s47, v135
	v_lshl_add_u64 v[10:11], v[130:131], 0, v[0:1]
	s_mov_b32 m0, s83
	v_add_u32_e32 v0, s47, v137
	global_load_lds_dwordx4 v[10:11], off
	v_lshl_add_u64 v[10:11], v[130:131], 0, v[0:1]
	s_add_i32 m0, s83, 0x2000
	s_nop 0
	global_load_lds_dwordx4 v[10:11], off
	s_mov_b32 m0, s18
	v_add_u32_e32 v0, s82, v134
	v_lshl_add_u64 v[10:11], v[130:131], 0, v[0:1]
	v_add_u32_e32 v0, s82, v136
	global_load_lds_dwordx4 v[10:11], off
	v_lshl_add_u64 v[10:11], v[130:131], 0, v[0:1]
	s_mov_b32 m0, s22
	s_nop 0
	global_load_lds_dwordx4 v[10:11], off
	s_waitcnt vmcnt(8)
	s_waitcnt lgkmcnt(0)
	s_barrier
	s_setprio 1
	s_waitcnt lgkmcnt(0)
	v_mfma_f32_16x16x128_f8f6f4 v[62:65], v[2:9], v[34:41], v[62:65]
	v_mfma_f32_16x16x128_f8f6f4 v[58:61], v[18:25], v[34:41], v[58:61]
	v_mfma_f32_16x16x128_f8f6f4 v[46:49], v[2:9], v[156:163], v[188:191]
	v_mfma_f32_16x16x128_f8f6f4 v[42:45], v[18:25], v[156:163], v[192:195]
	v_mfma_f32_16x16x128_f8f6f4 v[30:33], v[2:9], v[164:171], v[196:199]
	v_mfma_f32_16x16x128_f8f6f4 v[26:29], v[18:25], v[164:171], v[200:203]
	v_mfma_f32_16x16x128_f8f6f4 v[14:17], v[2:9], v[172:179], v[220:223]
	v_mfma_f32_16x16x128_f8f6f4 v[10:13], v[18:25], v[172:179], v[224:227]
	s_setprio 0
	s_setprio 1
	v_mfma_f32_16x16x128_f8f6f4 v[54:57], v[140:147], v[34:41], v[54:57]
	v_mfma_f32_16x16x128_f8f6f4 v[50:53], v[148:155], v[34:41], v[50:53]
	v_mfma_f32_16x16x128_f8f6f4 v[38:41], v[140:147], v[156:163], v[228:231]
	v_mfma_f32_16x16x128_f8f6f4 v[34:37], v[148:155], v[156:163], v[232:235]
	v_mfma_f32_16x16x128_f8f6f4 v[22:25], v[140:147], v[164:171], v[236:239]
	v_mfma_f32_16x16x128_f8f6f4 v[18:21], v[148:155], v[164:171], v[246:249]
	v_mfma_f32_16x16x128_f8f6f4 v[6:9], v[140:147], v[172:179], v[250:253]
	v_mfma_f32_16x16x128_f8f6f4 v[2:5], v[148:155], v[172:179], v[240:243]
	s_setprio 0
	s_barrier
	s_add_i32 s46, s46, 2
	s_addk_i32 s44, 0x100
	s_addk_i32 s45, 0x100
	s_cmp_gt_u32 s46, 29
	s_branch .LBB0_559
.Lf8_phase_end:
	v_readlane_b32 s4, v255, 6
	s_waitcnt vmcnt(0)
	v_readlane_b32 s5, v255, 7
	s_andn2_b64 vcc, exec, s[4:5]
	s_cbranch_vccnz .LBB0_563
	s_barrier
.LBB0_563:
	v_mov_b32_e32 v126, v245
	s_barrier
